# GEMM k-loops re-pipelined by hand: fragments of the next k-half/tile are read from LDS under the MFMAs of the current half, LDS-DMA for tile i+2 interleaved in the second half, one barrier per iterati
# speedup vs baseline: 1.0065x; 1.0063x over previous
; template <int EPI>
; __device__ __forceinline__ void gemm_tile(const bf16_t* __restrict__ A, const int lda, const bf16_t* __restrict__ Bt, const int ldb,
;                                           const int K, const int m0, const int n0, void* Cout, const int ldc, char* lds, const int tid) {
;     ...
;   const int nt = K >> 6;
;   const int st_row = tid >> 3, st_c = (tid & 7) ^ ((tid >> 4) & 7);
;   auto stageA = [&](int kt, int buf) {
; #pragma unroll
;     for (int i = 0; i < 4; ++i) {
;       const int off = tid * 16 + i * 4096, r = st_row + i * 32;
;       const bf16_t* ga = A + (size_t)(m0 + r) * lda + kt * 64 + st_c * 8;
;       __builtin_amdgcn_global_load_lds((const unsigned*)ga, (__attribute__((address_space(3))) unsigned*)(lds + buf * 32768 + off), 16, 0, 0);
;     }
;   };
;   auto stageB = [&](int kt, int buf) {
; #pragma unroll
;     for (int i = 0; i < 4; ++i) {
;       const int off = tid * 16 + i * 4096, r = st_row + i * 32;
;       const bf16_t* gb = Bt + (size_t)(n0 + r) * ldb + kt * 64 + st_c * 8;
;       __builtin_amdgcn_global_load_lds((const unsigned*)gb, (__attribute__((address_space(3))) unsigned*)(lds + buf * 32768 + 16384 + off), 16, 0, 0);
;     }
;   };
;   auto stage = [&](int kt, int buf) { stageA(kt, buf); stageB(kt, buf); };
;   const int fsw = (fr >> 1) & 7;
;   const int xk0 = (fq ^ fsw) << 4, xk1 = ((4 + fq) ^ fsw) << 4;
;   stage(0, 0);
;   for (int kt = 0; kt < nt; ++kt) {
;     asm volatile("s_waitcnt vmcnt(0)" ::: "memory");
;     __syncthreads();
;     if (kt + 1 < nt) stageB(kt + 1, (kt + 1) & 1);
;     const char* sa = lds + (kt & 1) * 32768;
;     const char* sb = sa + 16384;
;     bf16x8 af[2][4], bfr[2][4];
.LBB0_103:
	s_ashr_i32 s2, s24, 31
	s_lshr_b32 s2, s2, 27
	s_add_i32 s2, s24, s2
	s_ashr_i32 s3, s2, 5
	s_lshl_b32 s3, s3, 2
	s_sub_i32 s23, 0x85, s3
	s_min_u32 s23, s23, 4
	v_cvt_f32_ubyte0_e32 v4, s23
	v_rcp_iflag_f32_e32 v4, v4
	s_sub_i32 s29, 0, s23
	s_andn2_b32 s2, s2, 31
	s_sub_i32 s2, s24, s2
	v_mul_f32_e32 v4, 0x4f7ffffe, v4
	v_cvt_u32_f32_e32 v4, v4
	s_abs_i32 s27, s2
	s_ashr_i32 s25, s2, 31
	s_mov_b32 s26, 0
	v_readfirstlane_b32 s34, v4
	s_mul_i32 s29, s29, s34
	s_mul_hi_u32 s29, s34, s29
	s_add_i32 s34, s34, s29
	s_mul_hi_u32 s29, s27, s34
	s_mul_i32 s34, s29, s23
	s_sub_i32 s27, s27, s34
	s_add_i32 s34, s29, 1
	s_sub_i32 s35, s27, s23
	s_cmp_ge_u32 s27, s23
	s_cselect_b32 s29, s34, s29
	s_cselect_b32 s27, s35, s27
	s_add_i32 s34, s29, 1
	s_cmp_ge_u32 s27, s23
	s_cselect_b32 s27, s34, s29
	s_xor_b32 s27, s27, s25
	s_sub_i32 s25, s27, s25
	s_mul_i32 s23, s25, s23
	s_sub_i32 s2, s2, s23
	s_add_i32 s3, s3, s2
	s_lshl_b32 s3, s3, 7
	s_lshl_b32 s2, s25, 7
	v_add_u32_e32 v6, s3, v131
	s_movk_i32 s25, 0x1600
	v_readfirstlane_b32 s23, v176
	v_mad_i64_i32 v[4:5], s[34:35], v6, s25, v[0:1]
	s_mov_b32 m0, s23
	v_add_u32_e32 v7, s3, v177
	v_readfirstlane_b32 s23, v183
	global_load_lds_dwordx4 v[4:5], off
	v_mad_i64_i32 v[4:5], s[34:35], v7, s25, v[0:1]
	s_mov_b32 m0, s23
	v_add_u32_e32 v8, s3, v178
	v_readfirstlane_b32 s23, v184
	global_load_lds_dwordx4 v[4:5], off
	v_mad_i64_i32 v[4:5], s[34:35], v8, s25, v[0:1]
	s_mov_b32 m0, s23
	v_add_u32_e32 v9, s3, v179
	v_readfirstlane_b32 s23, v185
	global_load_lds_dwordx4 v[4:5], off
	v_mad_i64_i32 v[4:5], s[34:35], v9, s25, v[0:1]
	s_mov_b32 m0, s23
	v_add_u32_e32 v10, s2, v131
	v_readfirstlane_b32 s23, v186
	global_load_lds_dwordx4 v[4:5], off
	v_mad_i64_i32 v[4:5], s[34:35], v10, s25, v[132:133]
	s_mov_b32 m0, s23
	v_add_u32_e32 v11, s2, v177
	v_readfirstlane_b32 s23, v187
	global_load_lds_dwordx4 v[4:5], off
	v_mad_i64_i32 v[4:5], s[34:35], v11, s25, v[132:133]
	s_mov_b32 m0, s23
	v_add_u32_e32 v12, s2, v178
	v_readfirstlane_b32 s23, v188
	global_load_lds_dwordx4 v[4:5], off
	v_mad_i64_i32 v[4:5], s[34:35], v12, s25, v[132:133]
	s_mov_b32 m0, s23
	v_add_u32_e32 v13, s2, v179
	v_readfirstlane_b32 s23, v189
	global_load_lds_dwordx4 v[4:5], off
	v_mad_i64_i32 v[4:5], s[34:35], v13, s25, v[132:133]
	s_mov_b32 m0, s23
	v_mad_i64_i32 v[140:141], s[34:35], v10, s25, v[134:135]
	global_load_lds_dwordx4 v[4:5], off
	v_mad_i64_i32 v[142:143], s[34:35], v11, s25, v[134:135]
	v_mad_i64_i32 v[144:145], s[34:35], v12, s25, v[134:135]
	v_mad_i64_i32 v[146:147], s[34:35], v13, s25, v[134:135]
	v_mad_i64_i32 v[148:149], s[34:35], v6, s25, v[136:137]
	v_mad_i64_i32 v[150:151], s[34:35], v7, s25, v[136:137]
	v_mad_i64_i32 v[152:153], s[34:35], v8, s25, v[136:137]
	v_mad_i64_i32 v[154:155], s[34:35], v9, s25, v[136:137]
	v_mov_b32_e32 v4, 0
	s_mov_b64 s[34:35], 0
	v_mov_b32_e32 v5, v4
	v_mov_b32_e32 v6, v4
	v_mov_b32_e32 v7, v4
	v_mov_b32_e32 v12, v4
	v_mov_b32_e32 v13, v4
	v_mov_b32_e32 v14, v4
	v_mov_b32_e32 v15, v4
	s_waitcnt vmcnt(0)
	v_mov_b32_e32 v40, v4
	v_mov_b32_e32 v41, v4
	v_mov_b32_e32 v42, v4
	v_mov_b32_e32 v43, v4
	v_mov_b32_e32 v44, v4
	v_mov_b32_e32 v45, v4
	v_mov_b32_e32 v46, v4
	v_mov_b32_e32 v47, v4
	v_mov_b32_e32 v48, v4
	v_mov_b32_e32 v49, v4
	v_mov_b32_e32 v50, v4
	v_mov_b32_e32 v51, v4
	v_mov_b32_e32 v32, v4
	v_mov_b32_e32 v33, v4
	v_mov_b32_e32 v34, v4
	v_mov_b32_e32 v35, v4
	v_mov_b32_e32 v16, v4
	v_mov_b32_e32 v17, v4
	v_mov_b32_e32 v18, v4
	v_mov_b32_e32 v19, v4
	v_mov_b32_e32 v8, v4
	v_mov_b32_e32 v9, v4
	v_mov_b32_e32 v10, v4
	v_mov_b32_e32 v11, v4
	v_mov_b32_e32 v24, v4
	v_mov_b32_e32 v25, v4
	v_mov_b32_e32 v26, v4
	v_mov_b32_e32 v27, v4
	v_mov_b32_e32 v20, v4
	v_mov_b32_e32 v21, v4
	v_mov_b32_e32 v22, v4
	v_mov_b32_e32 v23, v4
	v_mov_b32_e32 v28, v4
	v_mov_b32_e32 v29, v4
	v_mov_b32_e32 v30, v4
	v_mov_b32_e32 v31, v4
	v_mov_b32_e32 v36, v4
	v_mov_b32_e32 v37, v4
	v_mov_b32_e32 v38, v4
	v_mov_b32_e32 v39, v4
	v_mov_b32_e32 v52, v4
	v_mov_b32_e32 v53, v4
	v_mov_b32_e32 v54, v4
	v_mov_b32_e32 v55, v4
	v_mov_b32_e32 v56, v4
	v_mov_b32_e32 v57, v4
	v_mov_b32_e32 v58, v4
	v_mov_b32_e32 v59, v4
	v_mov_b32_e32 v60, v4
	v_mov_b32_e32 v61, v4
	v_mov_b32_e32 v62, v4
	v_mov_b32_e32 v63, v4
	v_mov_b32_e32 v64, v4
	v_mov_b32_e32 v65, v4
	v_mov_b32_e32 v66, v4
	v_mov_b32_e32 v67, v4
	s_waitcnt vmcnt(0)
	s_barrier
	v_readfirstlane_b32 s100, v176
	s_add_i32 m0, s100, 0xc000
	v_lshl_add_u64 v[226:227], v[140:141], 0, s[34:35]
	global_load_lds_dwordx4 v[226:227], off
	s_add_i32 m0, s100, 0xd000
	v_lshl_add_u64 v[226:227], v[142:143], 0, s[34:35]
	global_load_lds_dwordx4 v[226:227], off
	s_add_i32 m0, s100, 0xe000
	v_lshl_add_u64 v[226:227], v[144:145], 0, s[34:35]
	global_load_lds_dwordx4 v[226:227], off
	s_add_i32 m0, s100, 0xf000
	v_lshl_add_u64 v[226:227], v[146:147], 0, s[34:35]
	global_load_lds_dwordx4 v[226:227], off
	s_add_i32 m0, s100, 0x8000
	v_lshl_add_u64 v[226:227], v[148:149], 0, s[34:35]
	global_load_lds_dwordx4 v[226:227], off
	s_add_i32 m0, s100, 0x9000
	v_lshl_add_u64 v[226:227], v[150:151], 0, s[34:35]
	global_load_lds_dwordx4 v[226:227], off
	s_add_i32 m0, s100, 0xa000
	v_lshl_add_u64 v[226:227], v[152:153], 0, s[34:35]
	global_load_lds_dwordx4 v[226:227], off
	s_add_i32 m0, s100, 0xb000
	v_lshl_add_u64 v[226:227], v[154:155], 0, s[34:35]
	global_load_lds_dwordx4 v[226:227], off
	v_add_u32_e32 v218, v174, v181
	v_add_u32_e32 v220, v174, v180
	ds_read_b128 v[104:107], v218
	ds_read_b128 v[100:103], v218 offset:2048
	ds_read_b128 v[96:99], v218 offset:4096
	ds_read_b128 v[84:87], v218 offset:6144
	ds_read_b128 v[190:193], v220 offset:16384
	ds_read_b128 v[194:197], v220 offset:18432
	ds_read_b128 v[198:201], v220 offset:20480
	ds_read_b128 v[202:205], v220 offset:22528
; template <int EPI>
; __device__ __forceinline__ void gemm_tile(const bf16_t* __restrict__ A, const int lda, const bf16_t* __restrict__ Bt, const int ldb,
;                                           const int K, const int m0, const int n0, void* Cout, const int ldc, char* lds, const int tid) {
;     ...
;   for (int kt = 0; kt < nt; ++kt) {
;     asm volatile("s_waitcnt vmcnt(0)" ::: "memory");
;     __syncthreads();
;     if (kt + 1 < nt) stageB(kt + 1, (kt + 1) & 1);
;     const char* sa = lds + (kt & 1) * 32768;
;     const char* sb = sa + 16384;
;     bf16x8 af[2][4], bfr[2][4];
; #pragma unroll
;     for (int ks = 0; ks < 2; ++ks) {
; #pragma unroll
;       for (int m = 0; m < 4; ++m) af[ks][m] = *(const bf16x8*)(sa + (wr * 64 + m * 16 + fr) * 128 + (ks ? xk1 : xk0));
; #pragma unroll
;       for (int n = 0; n < 4; ++n) bfr[ks][n] = *(const bf16x8*)(sb + (wc * 64 + n * 16 + fr) * 128 + (ks ? xk1 : xk0));
;     }
;     if (kt + 1 < nt) stageA(kt + 1, (kt + 1) & 1);
; #pragma unroll
;     for (int ks = 0; ks < 2; ++ks)
; #pragma unroll
;       for (int m = 0; m < 4; ++m)
; #pragma unroll
;         for (int n = 0; n < 4; ++n) acc[m][n] = __builtin_amdgcn_mfma_f32_16x16x32_bf16(bfr[ks][n], af[ks][m], acc[m][n], 0, 0, 0);
;   }
.LBB0_104:
	s_add_i32 s25, s26, 0x8000
	s_and_b32 s23, s25, 0x8000
	s_and_b32 s26, s26, 0x8000
	s_waitcnt lgkmcnt(0)
	v_mfma_f32_16x16x32_bf16 v[64:67], v[190:193], v[104:107], v[64:67]
	v_or_b32_e32 v216, s26, v175
	v_add_u32_e32 v222, v216, v181
	v_mfma_f32_16x16x32_bf16 v[60:63], v[194:197], v[104:107], v[60:63]
	v_add_u32_e32 v224, v216, v180
	ds_read_b128 v[206:209], v222
	v_mfma_f32_16x16x32_bf16 v[56:59], v[198:201], v[104:107], v[56:59]
	ds_read_b128 v[210:213], v222 offset:2048
	ds_read_b128 v[92:95], v222 offset:4096
	v_mfma_f32_16x16x32_bf16 v[52:55], v[202:205], v[104:107], v[52:55]
	ds_read_b128 v[68:71], v222 offset:6144
	ds_read_b128 v[88:91], v224 offset:16384
	v_mfma_f32_16x16x32_bf16 v[36:39], v[190:193], v[100:103], v[36:39]
	ds_read_b128 v[80:83], v224 offset:18432
	ds_read_b128 v[72:75], v224 offset:20480
	v_mfma_f32_16x16x32_bf16 v[28:31], v[194:197], v[100:103], v[28:31]
	ds_read_b128 v[76:79], v224 offset:22528
	v_or_b32_e32 v214, s23, v174
	v_mfma_f32_16x16x32_bf16 v[20:23], v[198:201], v[100:103], v[20:23]
	v_add_u32_e32 v218, v214, v181
	v_add_u32_e32 v220, v214, v180
	v_mfma_f32_16x16x32_bf16 v[24:27], v[202:205], v[100:103], v[24:27]
	v_readfirstlane_b32 s100, v176
	s_add_i32 s100, s100, s26
	v_mfma_f32_16x16x32_bf16 v[8:11], v[190:193], v[96:99], v[8:11]
	s_add_u32 s62, s34, 0x80
	s_addc_u32 s63, s35, 0
	v_mfma_f32_16x16x32_bf16 v[16:19], v[194:197], v[96:99], v[16:19]
	v_mfma_f32_16x16x32_bf16 v[32:35], v[198:201], v[96:99], v[32:35]
	v_mfma_f32_16x16x32_bf16 v[48:51], v[202:205], v[96:99], v[48:51]
	v_mfma_f32_16x16x32_bf16 v[44:47], v[190:193], v[84:87], v[44:47]
	v_mfma_f32_16x16x32_bf16 v[40:43], v[194:197], v[84:87], v[40:43]
	v_mfma_f32_16x16x32_bf16 v[12:15], v[198:201], v[84:87], v[12:15]
	v_mfma_f32_16x16x32_bf16 v[4:7], v[202:205], v[84:87], v[4:7]
	s_waitcnt vmcnt(0) lgkmcnt(0)
	s_barrier
	s_cmpk_eq_i32 s34, 0x1500
	s_cbranch_scc1 .Lr_last_104
	v_mfma_f32_16x16x32_bf16 v[64:67], v[88:91], v[206:209], v[64:67]
	s_add_i32 m0, s100, 0x4000
	v_lshl_add_u64 v[226:227], v[140:141], 0, s[62:63]
	global_load_lds_dwordx4 v[226:227], off
	v_mfma_f32_16x16x32_bf16 v[60:63], v[80:83], v[206:209], v[60:63]
	s_add_i32 m0, s100, 0x5000
	v_lshl_add_u64 v[226:227], v[142:143], 0, s[62:63]
	global_load_lds_dwordx4 v[226:227], off
	v_mfma_f32_16x16x32_bf16 v[56:59], v[72:75], v[206:209], v[56:59]
	s_add_i32 m0, s100, 0x6000
	v_lshl_add_u64 v[226:227], v[144:145], 0, s[62:63]
	global_load_lds_dwordx4 v[226:227], off
	v_mfma_f32_16x16x32_bf16 v[52:55], v[76:79], v[206:209], v[52:55]
	s_add_i32 m0, s100, 0x7000
	v_lshl_add_u64 v[226:227], v[146:147], 0, s[62:63]
	global_load_lds_dwordx4 v[226:227], off
	v_mfma_f32_16x16x32_bf16 v[36:39], v[88:91], v[210:213], v[36:39]
	s_mov_b32 m0, s100
	v_lshl_add_u64 v[226:227], v[148:149], 0, s[62:63]
	global_load_lds_dwordx4 v[226:227], off
	v_mfma_f32_16x16x32_bf16 v[28:31], v[80:83], v[210:213], v[28:31]
	s_add_i32 m0, s100, 0x1000
	v_lshl_add_u64 v[226:227], v[150:151], 0, s[62:63]
	global_load_lds_dwordx4 v[226:227], off
	v_mfma_f32_16x16x32_bf16 v[20:23], v[72:75], v[210:213], v[20:23]
	s_add_i32 m0, s100, 0x2000
	v_lshl_add_u64 v[226:227], v[152:153], 0, s[62:63]
	global_load_lds_dwordx4 v[226:227], off
	v_mfma_f32_16x16x32_bf16 v[24:27], v[76:79], v[210:213], v[24:27]
	s_add_i32 m0, s100, 0x3000
	v_lshl_add_u64 v[226:227], v[154:155], 0, s[62:63]
	global_load_lds_dwordx4 v[226:227], off
	v_mfma_f32_16x16x32_bf16 v[8:11], v[88:91], v[92:95], v[8:11]
	ds_read_b128 v[104:107], v218
	v_mfma_f32_16x16x32_bf16 v[16:19], v[80:83], v[92:95], v[16:19]
	ds_read_b128 v[100:103], v218 offset:2048
	v_mfma_f32_16x16x32_bf16 v[32:35], v[72:75], v[92:95], v[32:35]
	ds_read_b128 v[96:99], v218 offset:4096
	v_mfma_f32_16x16x32_bf16 v[48:51], v[76:79], v[92:95], v[48:51]
	ds_read_b128 v[84:87], v218 offset:6144
	v_mfma_f32_16x16x32_bf16 v[44:47], v[88:91], v[68:71], v[44:47]
	ds_read_b128 v[190:193], v220 offset:16384
	v_mfma_f32_16x16x32_bf16 v[40:43], v[80:83], v[68:71], v[40:43]
	ds_read_b128 v[194:197], v220 offset:18432
	v_mfma_f32_16x16x32_bf16 v[12:15], v[72:75], v[68:71], v[12:15]
	ds_read_b128 v[198:201], v220 offset:20480
	v_mfma_f32_16x16x32_bf16 v[4:7], v[76:79], v[68:71], v[4:7]
	ds_read_b128 v[202:205], v220 offset:22528
	s_add_u32 s34, s34, 0x80
	s_addc_u32 s35, s35, 0
	s_mov_b32 s26, s25
	s_branch .LBB0_104
.Lr_last_104:
	v_mfma_f32_16x16x32_bf16 v[64:67], v[88:91], v[206:209], v[64:67]
	v_mfma_f32_16x16x32_bf16 v[60:63], v[80:83], v[206:209], v[60:63]
	v_mfma_f32_16x16x32_bf16 v[56:59], v[72:75], v[206:209], v[56:59]
	v_mfma_f32_16x16x32_bf16 v[52:55], v[76:79], v[206:209], v[52:55]
	v_mfma_f32_16x16x32_bf16 v[36:39], v[88:91], v[210:213], v[36:39]
	v_mfma_f32_16x16x32_bf16 v[28:31], v[80:83], v[210:213], v[28:31]
	v_mfma_f32_16x16x32_bf16 v[20:23], v[72:75], v[210:213], v[20:23]
	v_mfma_f32_16x16x32_bf16 v[24:27], v[76:79], v[210:213], v[24:27]
	v_mfma_f32_16x16x32_bf16 v[8:11], v[88:91], v[92:95], v[8:11]
	v_mfma_f32_16x16x32_bf16 v[16:19], v[80:83], v[92:95], v[16:19]
	v_mfma_f32_16x16x32_bf16 v[32:35], v[72:75], v[92:95], v[32:35]
	v_mfma_f32_16x16x32_bf16 v[48:51], v[76:79], v[92:95], v[48:51]
	v_mfma_f32_16x16x32_bf16 v[44:47], v[88:91], v[68:71], v[44:47]
	v_mfma_f32_16x16x32_bf16 v[40:43], v[80:83], v[68:71], v[40:43]
	v_mfma_f32_16x16x32_bf16 v[12:15], v[72:75], v[68:71], v[12:15]
	v_mfma_f32_16x16x32_bf16 v[4:7], v[76:79], v[68:71], v[4:7]
	s_add_u32 s34, s34, 0x80
	s_addc_u32 s35, s35, 0
	s_mov_b32 s26, s25
	v_add_u32_e32 v84, s23, v174
	v_add_u32_e32 v80, v84, v181
	s_waitcnt vmcnt(0)
	s_waitcnt vmcnt(0) lgkmcnt(0)
	s_barrier
	ds_read_b128 v[68:71], v80
	ds_read_b128 v[72:75], v80 offset:2048
	ds_read_b128 v[76:79], v80 offset:4096
	ds_read_b128 v[80:83], v80 offset:6144
	v_add_u32_e32 v96, v84, v180
	ds_read_b128 v[84:87], v96 offset:16384
	ds_read_b128 v[88:91], v96 offset:18432
	ds_read_b128 v[92:95], v96 offset:20480
	ds_read_b128 v[96:99], v96 offset:22528
	v_add_u32_e32 v139, s23, v175
	v_add_u32_e32 v144, v139, v181
	s_waitcnt lgkmcnt(3)
	v_mfma_f32_16x16x32_bf16 v[36:39], v[84:87], v[72:75], v[36:39]
	ds_read_b128 v[100:103], v144
	ds_read_b128 v[104:107], v144 offset:2048
	ds_read_b128 v[140:143], v144 offset:4096
	ds_read_b128 v[144:147], v144 offset:6144
	v_add_u32_e32 v139, v139, v180
	ds_read_b128 v[148:151], v139 offset:16384
	ds_read_b128 v[152:155], v139 offset:18432
	ds_read_b128 v[190:193], v139 offset:20480
	ds_read_b128 v[194:197], v139 offset:22528
	v_mfma_f32_16x16x32_bf16 v[64:67], v[84:87], v[68:71], v[64:67]
	v_readlane_b32 s26, v253, 25
	v_readlane_b32 s27, v253, 26
	v_mov_b32_e32 v139, v3
	s_waitcnt lgkmcnt(10)
	v_mfma_f32_16x16x32_bf16 v[60:63], v[88:91], v[68:71], v[60:63]
	s_add_i32 s24, s24, s0
	s_cmpk_lg_i32 s0, 0x200
	s_cbranch_scc1 .Ltail_skip_1
	s_cmpk_lt_i32 s24, 0x400
	s_cbranch_scc1 .Ltail_skip_1
	s_cmpk_ge_i32 s24, 0x600
	s_cbranch_scc1 .Ltail_skip_1
	v_readlane_b32 s24, v254, 61
	s_nop 3
	s_addk_i32 s24, 0x400

; template <int EPI>
; __device__ __forceinline__ void gemm_tile(const bf16_t* __restrict__ A, const int lda, const bf16_t* __restrict__ Bt, const int ldb,
;                                           const int K, const int m0, const int n0, void* Cout, const int ldc, char* lds, const int tid) {
;     ...
;   f32x4 acc[4][4];
; #pragma unroll
;   for (int m = 0; m < 4; ++m)
; #pragma unroll
;     for (int n = 0; n < 4; ++n) acc[m][n] = (f32x4){0.f, 0.f, 0.f, 0.f};
;   const int nt = K >> 6;
;   const int st_row = tid >> 3, st_c = (tid & 7) ^ ((tid >> 4) & 7);
;   auto stageA = [&](int kt, int buf) {
; #pragma unroll
;     for (int i = 0; i < 4; ++i) {
;       const int off = tid * 16 + i * 4096, r = st_row + i * 32;
;       const bf16_t* ga = A + (size_t)(m0 + r) * lda + kt * 64 + st_c * 8;
;       __builtin_amdgcn_global_load_lds((const unsigned*)ga, (__attribute__((address_space(3))) unsigned*)(lds + buf * 32768 + off), 16, 0, 0);
;     }
;   };
;   auto stageB = [&](int kt, int buf) {
; #pragma unroll
;     for (int i = 0; i < 4; ++i) {
;       const int off = tid * 16 + i * 4096, r = st_row + i * 32;
;       const bf16_t* gb = Bt + (size_t)(n0 + r) * ldb + kt * 64 + st_c * 8;
;       __builtin_amdgcn_global_load_lds((const unsigned*)gb, (__attribute__((address_space(3))) unsigned*)(lds + buf * 32768 + 16384 + off), 16, 0, 0);
;     }
;   };
;   auto stage = [&](int kt, int buf) { stageA(kt, buf); stageB(kt, buf); };
;   const int fsw = (fr >> 1) & 7;
;   const int xk0 = (fq ^ fsw) << 4, xk1 = ((4 + fq) ^ fsw) << 4;
;   stage(0, 0);
; template <int EPI>
; __device__ __forceinline__ void gemm_phase(const bf16_t* A, int lda, const bf16_t* Bt, int ldb, int K, int ntn, void* C, int ldc, char* lds, int bid, int nb, const int tid) {
;   constexpr int GM = 4, nM = MT / 128;
;   const int ntiles = nM * ntn, nig = GM * ntn;
;   const int pos = (EPI != EPI_SWIGLU && (nb & 7) == 0) ? (bid & 7) * (nb >> 3) + (bid >> 3) : bid;
;   for (int L = pos; L < ntiles; L += nb) {
;     int mt, nn;
;     if (EPI == EPI_SWIGLU) { mt = L / ntn; nn = L % ntn; }
;     else { const int gid = L / nig, fm = gid * GM, gsz = min(nM - fm, GM), rem = L - gid * nig; mt = fm + rem % gsz; nn = rem / gsz; }
;     gemm_tile<EPI>(A, lda, Bt, ldb, K, mt * 128, nn * 128, C, ldc, lds, tid);
.LBB0_110:
	s_mul_hi_i32 s2, s23, 0x2e8ba2e9
	s_lshr_b32 s3, s2, 31
	s_ashr_i32 s2, s2, 3
	s_add_i32 s2, s2, s3
	s_lshl_b32 s25, s2, 7
	v_add_u32_e32 v4, s25, v174
	s_mul_i32 s3, s2, 44
	v_ashrrev_i32_e32 v5, 31, v4
	s_sub_i32 s24, s23, s3
	v_lshlrev_b64 v[4:5], 11, v[4:5]
	v_readfirstlane_b32 s3, v177
	v_lshl_add_u64 v[6:7], v[0:1], 0, v[4:5]
	s_mov_b32 m0, s3
	v_add_u32_e32 v2, 0x1000, v177
	global_load_lds_dwordx4 v[6:7], off
	v_add_u32_e32 v6, s25, v178
	v_ashrrev_i32_e32 v7, 31, v6
	v_lshlrev_b64 v[6:7], 11, v[6:7]
	v_readfirstlane_b32 s3, v2
	s_waitcnt vmcnt(0)
	v_lshl_add_u64 v[8:9], v[0:1], 0, v[6:7]
	s_mov_b32 m0, s3
	v_add_u32_e32 v2, 0x2000, v177
	global_load_lds_dwordx4 v[8:9], off
	v_add_u32_e32 v8, s25, v179
	v_ashrrev_i32_e32 v9, 31, v8
	v_lshlrev_b64 v[8:9], 11, v[8:9]
	v_readfirstlane_b32 s3, v2
	v_lshl_add_u64 v[10:11], v[0:1], 0, v[8:9]
	s_mov_b32 m0, s3
	v_add_u32_e32 v2, 0x3000, v177
	global_load_lds_dwordx4 v[10:11], off
	v_add_u32_e32 v10, s25, v180
	v_ashrrev_i32_e32 v11, 31, v10
	v_lshlrev_b64 v[10:11], 11, v[10:11]
	v_readfirstlane_b32 s3, v2
	s_lshl_b32 s2, s24, 7
	v_lshl_add_u64 v[12:13], v[0:1], 0, v[10:11]
	s_mov_b32 m0, s3
	v_add_u32_e32 v2, 0x4000, v177
	global_load_lds_dwordx4 v[12:13], off
	v_add_u32_e32 v12, s2, v174
	v_ashrrev_i32_e32 v13, 31, v12
	v_lshlrev_b64 v[12:13], 11, v[12:13]
	v_readfirstlane_b32 s3, v2
	v_lshl_add_u64 v[14:15], v[132:133], 0, v[12:13]
	s_mov_b32 m0, s3
	v_add_u32_e32 v2, 0x5000, v177
	global_load_lds_dwordx4 v[14:15], off
	v_add_u32_e32 v14, s2, v178
	v_ashrrev_i32_e32 v15, 31, v14
	v_lshlrev_b64 v[14:15], 11, v[14:15]
	v_readfirstlane_b32 s3, v2
	v_lshl_add_u64 v[16:17], v[132:133], 0, v[14:15]
	s_mov_b32 m0, s3
	v_add_u32_e32 v2, 0x6000, v177
	global_load_lds_dwordx4 v[16:17], off
	v_add_u32_e32 v16, s2, v179
	v_ashrrev_i32_e32 v17, 31, v16
	v_lshlrev_b64 v[16:17], 11, v[16:17]
	v_readfirstlane_b32 s3, v2
	v_lshl_add_u64 v[18:19], v[132:133], 0, v[16:17]
	s_mov_b32 m0, s3
	v_add_u32_e32 v2, 0x7000, v177
	global_load_lds_dwordx4 v[18:19], off
	v_add_u32_e32 v18, s2, v180
	v_ashrrev_i32_e32 v19, 31, v18
	v_lshlrev_b64 v[18:19], 11, v[18:19]
	v_readfirstlane_b32 s2, v2
	v_lshl_add_u64 v[20:21], v[132:133], 0, v[18:19]
	s_mov_b32 m0, s2
	v_lshl_add_u64 v[148:149], v[138:139], 0, v[4:5]
	global_load_lds_dwordx4 v[20:21], off
	v_mov_b32_e32 v4, 0
	v_lshl_add_u64 v[140:141], v[136:137], 0, v[12:13]
	v_lshl_add_u64 v[142:143], v[136:137], 0, v[14:15]
	v_lshl_add_u64 v[144:145], v[136:137], 0, v[16:17]
	v_lshl_add_u64 v[146:147], v[136:137], 0, v[18:19]
	v_lshl_add_u64 v[150:151], v[138:139], 0, v[6:7]
	v_lshl_add_u64 v[152:153], v[138:139], 0, v[8:9]
	v_lshl_add_u64 v[154:155], v[138:139], 0, v[10:11]
	s_mov_b32 s27, 0
	s_mov_b64 s[2:3], 0
	v_mov_b32_e32 v5, v4
	v_mov_b32_e32 v6, v4
	v_mov_b32_e32 v7, v4
	v_mov_b32_e32 v8, v4
	v_mov_b32_e32 v9, v4
	v_mov_b32_e32 v10, v4
	v_mov_b32_e32 v11, v4
	v_mov_b32_e32 v12, v4
	v_mov_b32_e32 v13, v4
	v_mov_b32_e32 v14, v4
	v_mov_b32_e32 v15, v4
	v_mov_b32_e32 v16, v4
	v_mov_b32_e32 v17, v4
	v_mov_b32_e32 v18, v4
	v_mov_b32_e32 v19, v4
	v_mov_b32_e32 v20, v4
	v_mov_b32_e32 v21, v4
	v_mov_b32_e32 v22, v4
	v_mov_b32_e32 v23, v4
	v_mov_b32_e32 v28, v4
	v_mov_b32_e32 v29, v4
	v_mov_b32_e32 v30, v4
	v_mov_b32_e32 v31, v4
	v_mov_b32_e32 v24, v4
	v_mov_b32_e32 v25, v4
	v_mov_b32_e32 v26, v4
	v_mov_b32_e32 v27, v4
	v_mov_b32_e32 v32, v4
	v_mov_b32_e32 v33, v4
	v_mov_b32_e32 v34, v4
	v_mov_b32_e32 v35, v4
	v_mov_b32_e32 v40, v4
	v_mov_b32_e32 v41, v4
	v_mov_b32_e32 v42, v4
	v_mov_b32_e32 v43, v4
	v_mov_b32_e32 v36, v4
	v_mov_b32_e32 v37, v4
	v_mov_b32_e32 v38, v4
	v_mov_b32_e32 v39, v4
	v_mov_b32_e32 v44, v4
	v_mov_b32_e32 v45, v4
	v_mov_b32_e32 v46, v4
	v_mov_b32_e32 v47, v4
	v_mov_b32_e32 v48, v4
	v_mov_b32_e32 v49, v4
	v_mov_b32_e32 v50, v4
	v_mov_b32_e32 v51, v4
	v_mov_b32_e32 v52, v4
	v_mov_b32_e32 v53, v4
	v_mov_b32_e32 v54, v4
	v_mov_b32_e32 v55, v4
	v_mov_b32_e32 v56, v4
	v_mov_b32_e32 v57, v4
	v_mov_b32_e32 v58, v4
	v_mov_b32_e32 v59, v4
	v_mov_b32_e32 v60, v4
	v_mov_b32_e32 v61, v4
	v_mov_b32_e32 v62, v4
	v_mov_b32_e32 v63, v4
	v_mov_b32_e32 v64, v4
	v_mov_b32_e32 v65, v4
	v_mov_b32_e32 v66, v4
	v_mov_b32_e32 v67, v4
	s_waitcnt vmcnt(0)
	s_barrier
	v_readfirstlane_b32 s100, v177
	s_add_i32 m0, s100, 0xc000
	v_lshl_add_u64 v[226:227], v[140:141], 0, s[2:3]
	global_load_lds_dwordx4 v[226:227], off
	s_add_i32 m0, s100, 0xd000
	v_lshl_add_u64 v[226:227], v[142:143], 0, s[2:3]
	global_load_lds_dwordx4 v[226:227], off
	s_add_i32 m0, s100, 0xe000
	v_lshl_add_u64 v[226:227], v[144:145], 0, s[2:3]
	global_load_lds_dwordx4 v[226:227], off
	s_add_i32 m0, s100, 0xf000
	v_lshl_add_u64 v[226:227], v[146:147], 0, s[2:3]
	global_load_lds_dwordx4 v[226:227], off
	s_add_i32 m0, s100, 0x8000
	v_lshl_add_u64 v[226:227], v[148:149], 0, s[2:3]
	global_load_lds_dwordx4 v[226:227], off
	s_add_i32 m0, s100, 0x9000
	v_lshl_add_u64 v[226:227], v[150:151], 0, s[2:3]
	global_load_lds_dwordx4 v[226:227], off
	s_add_i32 m0, s100, 0xa000
	v_lshl_add_u64 v[226:227], v[152:153], 0, s[2:3]
	global_load_lds_dwordx4 v[226:227], off
	s_add_i32 m0, s100, 0xb000
	v_lshl_add_u64 v[226:227], v[154:155], 0, s[2:3]
	global_load_lds_dwordx4 v[226:227], off
	v_add_u32_e32 v218, v175, v182
	v_add_u32_e32 v220, v175, v181
	ds_read_b128 v[104:107], v218
	ds_read_b128 v[100:103], v218 offset:2048
	ds_read_b128 v[96:99], v218 offset:4096
	ds_read_b128 v[84:87], v218 offset:6144
	ds_read_b128 v[184:187], v220 offset:16384
	ds_read_b128 v[188:191], v220 offset:18432
	ds_read_b128 v[192:195], v220 offset:20480
	ds_read_b128 v[196:199], v220 offset:22528
; template <int EPI>
; __device__ __forceinline__ void gemm_tile(const bf16_t* __restrict__ A, const int lda, const bf16_t* __restrict__ Bt, const int ldb,
;                                           const int K, const int m0, const int n0, void* Cout, const int ldc, char* lds, const int tid) {
;     ...
;   for (int kt = 0; kt < nt; ++kt) {
;     asm volatile("s_waitcnt vmcnt(0)" ::: "memory");
;     __syncthreads();
;     if (kt + 1 < nt) stageB(kt + 1, (kt + 1) & 1);
;     const char* sa = lds + (kt & 1) * 32768;
;     const char* sb = sa + 16384;
;     bf16x8 af[2][4], bfr[2][4];
; #pragma unroll
;     for (int ks = 0; ks < 2; ++ks) {
; #pragma unroll
;       for (int m = 0; m < 4; ++m) af[ks][m] = *(const bf16x8*)(sa + (wr * 64 + m * 16 + fr) * 128 + (ks ? xk1 : xk0));
; #pragma unroll
;       for (int n = 0; n < 4; ++n) bfr[ks][n] = *(const bf16x8*)(sb + (wc * 64 + n * 16 + fr) * 128 + (ks ? xk1 : xk0));
;     }
;     if (kt + 1 < nt) stageA(kt + 1, (kt + 1) & 1);
; #pragma unroll
;     for (int ks = 0; ks < 2; ++ks)
; #pragma unroll
;       for (int m = 0; m < 4; ++m)
; #pragma unroll
;         for (int n = 0; n < 4; ++n) acc[m][n] = __builtin_amdgcn_mfma_f32_16x16x32_bf16(bfr[ks][n], af[ks][m], acc[m][n], 0, 0, 0);
;   }
.LBB0_111:
	s_add_i32 s26, s27, 0x8000
	s_and_b32 s29, s26, 0x8000
	s_and_b32 s27, s27, 0x8000
	s_waitcnt lgkmcnt(0)
	v_mfma_f32_16x16x32_bf16 v[64:67], v[184:187], v[104:107], v[64:67]
	v_or_b32_e32 v216, s27, v176
	v_add_u32_e32 v222, v216, v182
	v_mfma_f32_16x16x32_bf16 v[60:63], v[188:191], v[104:107], v[60:63]
	v_add_u32_e32 v224, v216, v181
	ds_read_b128 v[200:203], v222
	v_mfma_f32_16x16x32_bf16 v[56:59], v[192:195], v[104:107], v[56:59]
	ds_read_b128 v[204:207], v222 offset:2048
	ds_read_b128 v[92:95], v222 offset:4096
	v_mfma_f32_16x16x32_bf16 v[52:55], v[196:199], v[104:107], v[52:55]
	ds_read_b128 v[68:71], v222 offset:6144
	ds_read_b128 v[88:91], v224 offset:16384
	v_mfma_f32_16x16x32_bf16 v[48:51], v[184:187], v[100:103], v[48:51]
	ds_read_b128 v[80:83], v224 offset:18432
	ds_read_b128 v[72:75], v224 offset:20480
	v_mfma_f32_16x16x32_bf16 v[44:47], v[188:191], v[100:103], v[44:47]
	ds_read_b128 v[76:79], v224 offset:22528
	v_or_b32_e32 v214, s29, v175
	v_mfma_f32_16x16x32_bf16 v[36:39], v[192:195], v[100:103], v[36:39]
	v_add_u32_e32 v218, v214, v182
	v_add_u32_e32 v220, v214, v181
	v_mfma_f32_16x16x32_bf16 v[40:43], v[196:199], v[100:103], v[40:43]
	v_readfirstlane_b32 s100, v177
	s_add_i32 s100, s100, s27
	v_mfma_f32_16x16x32_bf16 v[32:35], v[184:187], v[96:99], v[32:35]
	s_add_u32 s62, s2, 0x80
	s_addc_u32 s63, s3, 0
	v_mfma_f32_16x16x32_bf16 v[24:27], v[188:191], v[96:99], v[24:27]
	v_mfma_f32_16x16x32_bf16 v[28:31], v[192:195], v[96:99], v[28:31]
	v_mfma_f32_16x16x32_bf16 v[20:23], v[196:199], v[96:99], v[20:23]
	v_mfma_f32_16x16x32_bf16 v[16:19], v[184:187], v[84:87], v[16:19]
	v_mfma_f32_16x16x32_bf16 v[12:15], v[188:191], v[84:87], v[12:15]
	v_mfma_f32_16x16x32_bf16 v[8:11], v[192:195], v[84:87], v[8:11]
	v_mfma_f32_16x16x32_bf16 v[4:7], v[196:199], v[84:87], v[4:7]
	s_waitcnt vmcnt(0) lgkmcnt(0)
	s_barrier
	s_cmpk_eq_i32 s2, 0x700
	s_cbranch_scc1 .Lr_last_111
	v_mfma_f32_16x16x32_bf16 v[64:67], v[88:91], v[200:203], v[64:67]
	s_add_i32 m0, s100, 0x4000
	v_lshl_add_u64 v[226:227], v[140:141], 0, s[62:63]
	global_load_lds_dwordx4 v[226:227], off
	v_mfma_f32_16x16x32_bf16 v[60:63], v[80:83], v[200:203], v[60:63]
	s_add_i32 m0, s100, 0x5000
	v_lshl_add_u64 v[226:227], v[142:143], 0, s[62:63]
	global_load_lds_dwordx4 v[226:227], off
	v_mfma_f32_16x16x32_bf16 v[56:59], v[72:75], v[200:203], v[56:59]
	s_add_i32 m0, s100, 0x6000
	v_lshl_add_u64 v[226:227], v[144:145], 0, s[62:63]
	global_load_lds_dwordx4 v[226:227], off
	v_mfma_f32_16x16x32_bf16 v[52:55], v[76:79], v[200:203], v[52:55]
	s_add_i32 m0, s100, 0x7000
	v_lshl_add_u64 v[226:227], v[146:147], 0, s[62:63]
	global_load_lds_dwordx4 v[226:227], off
	v_mfma_f32_16x16x32_bf16 v[48:51], v[88:91], v[204:207], v[48:51]
	s_mov_b32 m0, s100
	v_lshl_add_u64 v[226:227], v[148:149], 0, s[62:63]
	global_load_lds_dwordx4 v[226:227], off
	v_mfma_f32_16x16x32_bf16 v[44:47], v[80:83], v[204:207], v[44:47]
	s_add_i32 m0, s100, 0x1000
	v_lshl_add_u64 v[226:227], v[150:151], 0, s[62:63]
	global_load_lds_dwordx4 v[226:227], off
	v_mfma_f32_16x16x32_bf16 v[36:39], v[72:75], v[204:207], v[36:39]
	s_add_i32 m0, s100, 0x2000
	v_lshl_add_u64 v[226:227], v[152:153], 0, s[62:63]
	global_load_lds_dwordx4 v[226:227], off
	v_mfma_f32_16x16x32_bf16 v[40:43], v[76:79], v[204:207], v[40:43]
	s_add_i32 m0, s100, 0x3000
	v_lshl_add_u64 v[226:227], v[154:155], 0, s[62:63]
	global_load_lds_dwordx4 v[226:227], off
	v_mfma_f32_16x16x32_bf16 v[32:35], v[88:91], v[92:95], v[32:35]
	ds_read_b128 v[104:107], v218
	v_mfma_f32_16x16x32_bf16 v[24:27], v[80:83], v[92:95], v[24:27]
	ds_read_b128 v[100:103], v218 offset:2048
	v_mfma_f32_16x16x32_bf16 v[28:31], v[72:75], v[92:95], v[28:31]
	ds_read_b128 v[96:99], v218 offset:4096
	v_mfma_f32_16x16x32_bf16 v[20:23], v[76:79], v[92:95], v[20:23]
	ds_read_b128 v[84:87], v218 offset:6144
	v_mfma_f32_16x16x32_bf16 v[16:19], v[88:91], v[68:71], v[16:19]
	ds_read_b128 v[184:187], v220 offset:16384
	v_mfma_f32_16x16x32_bf16 v[12:15], v[80:83], v[68:71], v[12:15]
	ds_read_b128 v[188:191], v220 offset:18432
	v_mfma_f32_16x16x32_bf16 v[8:11], v[72:75], v[68:71], v[8:11]
	ds_read_b128 v[192:195], v220 offset:20480
	v_mfma_f32_16x16x32_bf16 v[4:7], v[76:79], v[68:71], v[4:7]
	ds_read_b128 v[196:199], v220 offset:22528
	s_add_u32 s2, s2, 0x80
	s_addc_u32 s3, s3, 0
	s_mov_b32 s27, s26
	s_branch .LBB0_111
; __device__ __forceinline__ unsigned pk2(float lo, float hi) { const f32x2_t v = {lo, hi}; const bf16x2_t b = __builtin_convertvector(v, bf16x2_t); return __builtin_bit_cast(unsigned, b); }
; __device__ __forceinline__ float siluf_(float x) { return x * __builtin_amdgcn_rcpf(1.0f + __expf(-x)); }
; template <int EPI>
; __device__ __forceinline__ void gemm_tile(const bf16_t* __restrict__ A, const int lda, const bf16_t* __restrict__ Bt, const int ldb,
;                                           const int K, const int m0, const int n0, void* Cout, const int ldc, char* lds, const int tid) {
;     ...
; #pragma unroll
;     for (int ks = 0; ks < 2; ++ks)
; #pragma unroll
;       for (int m = 0; m < 4; ++m)
; #pragma unroll
;         for (int n = 0; n < 4; ++n) acc[m][n] = __builtin_amdgcn_mfma_f32_16x16x32_bf16(bfr[ks][n], af[ks][m], acc[m][n], 0, 0, 0);
;   }
;     ...
; #pragma unroll
;   for (int m = 0; m < 4; ++m) {
;     const int row = m0 + wr * 64 + m * 16 + fr;
;     if (EPI == EPI_BF16) {
;       bf16_t* C = (bf16_t*)Cout + (size_t)row * ldc + n0 + wc * 64 + fq * 8;
; #pragma unroll
;       for (int pq = 0; pq < 2; ++pq) { uint4 o; o.x = pk2(acc[m][2 * pq][0], acc[m][2 * pq][1]); o.y = pk2(acc[m][2 * pq][2], acc[m][2 * pq][3]);
;         o.z = pk2(acc[m][2 * pq + 1][0], acc[m][2 * pq + 1][1]); o.w = pk2(acc[m][2 * pq + 1][2], acc[m][2 * pq + 1][3]); *(uint4*)(C + pq * 32) = o; }
;     } else if (EPI == EPI_RESID) {
;       float* C = (float*)Cout + (size_t)row * ldc + n0 + wc * 64 + fq * 4;
; #pragma unroll
;       for (int n = 0; n < 4; ++n) { const f32x4 x = *(const f32x4*)(C + n * 16); *(f32x4*)(C + n * 16) = x * ALPHA + acc[m][n]; }
;     } else {
;       bf16_t* C = (bf16_t*)Cout + (size_t)row * ldc + (n0 >> 1) + wc * 32 + fq * 8;
;       const f32x4 g0 = acc[m][0], u0 = acc[m][1], g1 = acc[m][2], u1 = acc[m][3];
;       uint4 o; o.x = pk2(siluf_(g0[0]) * u0[0], siluf_(g0[1]) * u0[1]); o.y = pk2(siluf_(g0[2]) * u0[2], siluf_(g0[3]) * u0[3]);
;       o.z = pk2(siluf_(g1[0]) * u1[0], siluf_(g1[1]) * u1[1]); o.w = pk2(siluf_(g1[2]) * u1[2], siluf_(g1[3]) * u1[3]);
;       *(uint4*)C = o;
.Lr_last_111:
	v_mfma_f32_16x16x32_bf16 v[64:67], v[88:91], v[200:203], v[64:67]
	v_mfma_f32_16x16x32_bf16 v[60:63], v[80:83], v[200:203], v[60:63]
	v_mfma_f32_16x16x32_bf16 v[56:59], v[72:75], v[200:203], v[56:59]
	v_mfma_f32_16x16x32_bf16 v[52:55], v[76:79], v[200:203], v[52:55]
	v_mfma_f32_16x16x32_bf16 v[48:51], v[88:91], v[204:207], v[48:51]
	v_mfma_f32_16x16x32_bf16 v[44:47], v[80:83], v[204:207], v[44:47]
	v_mfma_f32_16x16x32_bf16 v[36:39], v[72:75], v[204:207], v[36:39]
	v_mfma_f32_16x16x32_bf16 v[40:43], v[76:79], v[204:207], v[40:43]
	v_mfma_f32_16x16x32_bf16 v[32:35], v[88:91], v[92:95], v[32:35]
	v_mfma_f32_16x16x32_bf16 v[24:27], v[80:83], v[92:95], v[24:27]
	v_mfma_f32_16x16x32_bf16 v[28:31], v[72:75], v[92:95], v[28:31]
	v_mfma_f32_16x16x32_bf16 v[20:23], v[76:79], v[92:95], v[20:23]
	v_mfma_f32_16x16x32_bf16 v[16:19], v[88:91], v[68:71], v[16:19]
	v_mfma_f32_16x16x32_bf16 v[12:15], v[80:83], v[68:71], v[12:15]
	v_mfma_f32_16x16x32_bf16 v[8:11], v[72:75], v[68:71], v[8:11]
	v_mfma_f32_16x16x32_bf16 v[4:7], v[76:79], v[68:71], v[4:7]
	s_add_u32 s2, s2, 0x80
	s_addc_u32 s3, s3, 0
	s_mov_b32 s27, s26
	v_add_u32_e32 v2, v175, v181
	s_waitcnt vmcnt(0)
	s_waitcnt vmcnt(0) lgkmcnt(0)
	s_barrier
	ds_read_b128 v[68:71], v2 offset:49152
	v_add_u32_e32 v92, v175, v182
	ds_read_b128 v[72:75], v2 offset:51200
	ds_read_b128 v[76:79], v92 offset:32768
	ds_read_b128 v[80:83], v92 offset:34816
	ds_read_b128 v[84:87], v2 offset:53248
	ds_read_b128 v[88:91], v2 offset:55296
	v_add_u32_e32 v2, v176, v182
	s_waitcnt lgkmcnt(3)
	v_mfma_f32_16x16x32_bf16 v[64:67], v[68:71], v[76:79], v[64:67]
	s_lshl_b32 s2, s24, 6
	s_ashr_i32 s3, s2, 31
	s_movk_i32 s24, 0x1600
	v_mfma_f32_16x16x32_bf16 v[60:63], v[72:75], v[76:79], v[60:63]
	s_add_i32 s23, s23, s0
	s_cmpk_gt_i32 s23, 0x16db
	s_waitcnt lgkmcnt(1)
	v_mfma_f32_16x16x32_bf16 v[56:59], v[84:87], v[76:79], v[56:59]
	s_waitcnt lgkmcnt(0)
	v_mfma_f32_16x16x32_bf16 v[52:55], v[88:91], v[76:79], v[52:55]
	ds_read_b128 v[76:79], v92 offset:36864
	ds_read_b128 v[92:95], v92 offset:38912
	ds_read_b128 v[96:99], v2 offset:32768
	ds_read_b128 v[100:103], v2 offset:34816
	ds_read_b128 v[104:107], v2 offset:36864
	ds_read_b128 v[140:143], v2 offset:38912
	v_add_u32_e32 v2, v176, v181
	ds_read_b128 v[144:147], v2 offset:49152
	ds_read_b128 v[148:151], v2 offset:51200
	s_waitcnt lgkmcnt(1)
	v_mfma_f32_16x16x32_bf16 v[64:67], v[144:147], v[96:99], v[64:67]
	v_mfma_f32_16x16x32_bf16 v[184:187], v[68:71], v[76:79], v[32:35]
	s_nop 6
	v_mul_f32_e32 v34, 0xbfb8aa3b, v64
	v_mul_f32_e32 v35, 0xbfb8aa3b, v65
	v_exp_f32_e32 v34, v34
	v_exp_f32_e32 v35, v35
	s_waitcnt lgkmcnt(0)
	v_mfma_f32_16x16x32_bf16 v[60:63], v[148:151], v[96:99], v[60:63]
	v_lshl_add_u64 v[32:33], s[2:3], 1, v[134:135]
	v_add_f32_e32 v34, 1.0, v34
	v_add_f32_e32 v35, 1.0, v35
	v_rcp_f32_e32 v34, v34
	v_rcp_f32_e32 v35, v35
	v_mfma_f32_16x16x32_bf16 v[48:51], v[68:71], v[80:83], v[48:51]
	v_mul_f32_e64 v34, v64, v34
	v_mul_f32_e64 v35, v65, v35
	v_mfma_f32_16x16x32_bf16 v[44:47], v[72:75], v[80:83], v[44:47]
	v_mul_f32_e64 v34, v60, v34
	v_mul_f32_e64 v35, v61, v35
	v_mul_f32_e32 v60, 0xbfb8aa3b, v67
	v_cvt_pk_bf16_f32 v34, v34, v35
	v_mfma_f32_16x16x32_bf16 v[36:39], v[84:87], v[80:83], v[36:39]
	v_mul_f32_e32 v35, 0xbfb8aa3b, v66
	v_exp_f32_e32 v35, v35
	v_exp_f32_e32 v61, v60
	v_mfma_f32_16x16x32_bf16 v[40:43], v[88:91], v[80:83], v[40:43]
	ds_read_b128 v[80:83], v2 offset:53248
	ds_read_b128 v[152:155], v2 offset:55296
	v_add_f32_e32 v35, 1.0, v35
	v_rcp_f32_e32 v60, v35
	s_waitcnt lgkmcnt(1)
	v_mfma_f32_16x16x32_bf16 v[56:59], v[80:83], v[96:99], v[56:59]
	v_add_f32_e32 v35, 1.0, v61
	v_rcp_f32_e32 v61, v35
	v_or_b32_e32 v2, s25, v131
	s_waitcnt lgkmcnt(0)
; __device__ __forceinline__ unsigned pk2(float lo, float hi) { const f32x2_t v = {lo, hi}; const bf16x2_t b = __builtin_convertvector(v, bf16x2_t); return __builtin_bit_cast(unsigned, b); }
; __device__ __forceinline__ float siluf_(float x) { return x * __builtin_amdgcn_rcpf(1.0f + __expf(-x)); }
; template <int EPI>
; __device__ __forceinline__ void gemm_tile(const bf16_t* __restrict__ A, const int lda, const bf16_t* __restrict__ Bt, const int ldb,
;                                           const int K, const int m0, const int n0, void* Cout, const int ldc, char* lds, const int tid) {
;     ...
; #pragma unroll
;   for (int m = 0; m < 4; ++m) {
;     const int row = m0 + wr * 64 + m * 16 + fr;
;     if (EPI == EPI_BF16) {
;       bf16_t* C = (bf16_t*)Cout + (size_t)row * ldc + n0 + wc * 64 + fq * 8;
; #pragma unroll
;       for (int pq = 0; pq < 2; ++pq) { uint4 o; o.x = pk2(acc[m][2 * pq][0], acc[m][2 * pq][1]); o.y = pk2(acc[m][2 * pq][2], acc[m][2 * pq][3]);
;         o.z = pk2(acc[m][2 * pq + 1][0], acc[m][2 * pq + 1][1]); o.w = pk2(acc[m][2 * pq + 1][2], acc[m][2 * pq + 1][3]); *(uint4*)(C + pq * 32) = o; }
;     } else if (EPI == EPI_RESID) {
;       float* C = (float*)Cout + (size_t)row * ldc + n0 + wc * 64 + fq * 4;
; #pragma unroll
;       for (int n = 0; n < 4; ++n) { const f32x4 x = *(const f32x4*)(C + n * 16); *(f32x4*)(C + n * 16) = x * ALPHA + acc[m][n]; }
;     } else {
;       bf16_t* C = (bf16_t*)Cout + (size_t)row * ldc + (n0 >> 1) + wc * 32 + fq * 8;
;       const f32x4 g0 = acc[m][0], u0 = acc[m][1], g1 = acc[m][2], u1 = acc[m][3];
;       uint4 o; o.x = pk2(siluf_(g0[0]) * u0[0], siluf_(g0[1]) * u0[1]); o.y = pk2(siluf_(g0[2]) * u0[2], siluf_(g0[3]) * u0[3]);
;       o.z = pk2(siluf_(g1[0]) * u1[0], siluf_(g1[1]) * u1[1]); o.w = pk2(siluf_(g1[2]) * u1[2], siluf_(g1[3]) * u1[3]);
;       *(uint4*)C = o;
	v_mfma_f32_16x16x32_bf16 v[52:55], v[152:155], v[96:99], v[52:55]
	s_nop 2
	v_mul_f32_e32 v35, 0xbfb8aa3b, v56
	v_exp_f32_e32 v35, v35
	v_mul_f32_e32 v64, 0xbfb8aa3b, v57
	v_exp_f32_e32 v65, v64
	v_pk_mul_f32 v[60:61], v[66:67], v[60:61]
	v_add_f32_e32 v35, 1.0, v35
	v_rcp_f32_e32 v64, v35
	v_add_f32_e32 v35, 1.0, v65
	v_rcp_f32_e32 v65, v35
	v_pk_mul_f32 v[60:61], v[62:63], v[60:61]
	v_mfma_f32_16x16x32_bf16 v[48:51], v[144:147], v[100:103], v[48:51]
	v_cvt_pk_bf16_f32 v35, v60, v61
	v_mul_f32_e32 v60, 0xbfb8aa3b, v58
	v_exp_f32_e32 v60, v60
	v_mul_f32_e32 v61, 0xbfb8aa3b, v59
	v_pk_mul_f32 v[56:57], v[56:57], v[64:65]
	v_exp_f32_e32 v65, v61
	v_add_f32_e32 v60, 1.0, v60
	v_rcp_f32_e32 v64, v60
	v_mfma_f32_16x16x32_bf16 v[60:63], v[80:83], v[100:103], v[36:39]
	v_add_u32_e32 v2, v2, v183
	v_mad_i64_i32 v[158:159], s[2:3], v2, s24, v[32:33]
	s_nop 0
	v_add_f32_e32 v36, 1.0, v65
	v_rcp_f32_e32 v65, v36
	v_mfma_f32_16x16x32_bf16 v[38:41], v[152:155], v[100:103], v[40:43]
	v_mul_f32_e64 v36, v52, v56
	v_mul_f32_e64 v37, v53, v57
	v_cvt_pk_bf16_f32 v36, v36, v37
	v_pk_mul_f32 v[42:43], v[58:59], v[64:65]
	v_mfma_f32_16x16x32_bf16 v[44:47], v[148:151], v[100:103], v[44:47]
	v_mul_f32_e64 v42, v54, v42
	v_mul_f32_e64 v43, v55, v43
	v_cvt_pk_bf16_f32 v37, v42, v43
	global_store_dwordx4 v[158:159], v[34:37], off
	v_mfma_f32_16x16x32_bf16 v[52:55], v[144:147], v[104:107], v[184:187]
	s_nop 0
	v_or_b32_e32 v34, 16, v2
	v_mad_i64_i32 v[42:43], s[2:3], v34, s24, v[32:33]
	v_mul_f32_e32 v34, 0xbfb8aa3b, v48
	v_mul_f32_e32 v35, 0xbfb8aa3b, v49
	v_exp_f32_e32 v34, v34
	v_exp_f32_e32 v35, v35
	v_mul_f32_e32 v36, 0xbfb8aa3b, v50
	v_mul_f32_e32 v37, 0xbfb8aa3b, v51
	v_add_f32_e32 v34, 1.0, v34
	v_add_f32_e32 v35, 1.0, v35
	v_rcp_f32_e32 v34, v34
	v_rcp_f32_e32 v35, v35
	v_exp_f32_e32 v36, v36
	v_exp_f32_e32 v37, v37
	v_mfma_f32_16x16x32_bf16 v[24:27], v[72:75], v[76:79], v[24:27]
	v_mul_f32_e64 v34, v48, v34
	v_mul_f32_e64 v35, v49, v35
	v_add_f32_e32 v36, 1.0, v36
	v_add_f32_e32 v37, 1.0, v37
	v_pk_mul_f32 v[34:35], v[44:45], v[34:35]
	v_rcp_f32_e32 v36, v36
	v_rcp_f32_e32 v37, v37
	v_cvt_pk_bf16_f32 v34, v34, v35
	v_mul_f32_e32 v35, 0xbfb8aa3b, v60
	v_exp_f32_e32 v44, v35
	v_mul_f32_e32 v35, 0xbfb8aa3b, v61
	v_exp_f32_e32 v45, v35
	v_pk_mul_f32 v[36:37], v[50:51], v[36:37]
	v_mfma_f32_16x16x32_bf16 v[28:31], v[84:87], v[76:79], v[28:31]
	v_mul_f32_e64 v36, v46, v36
	v_mul_f32_e64 v37, v47, v37
	v_cvt_pk_bf16_f32 v35, v36, v37
	v_add_f32_e32 v36, 1.0, v44
	v_add_f32_e32 v37, 1.0, v45
	v_mul_f32_e32 v44, 0xbfb8aa3b, v62
	v_mul_f32_e32 v45, 0xbfb8aa3b, v63
	v_exp_f32_e32 v44, v44
	v_exp_f32_e32 v45, v45
	v_rcp_f32_e32 v36, v36
	v_rcp_f32_e32 v37, v37
	v_add_f32_e32 v44, 1.0, v44
	v_add_f32_e32 v45, 1.0, v45
	v_rcp_f32_e32 v44, v44
	v_rcp_f32_e32 v45, v45
	v_pk_mul_f32 v[36:37], v[60:61], v[36:37]
	v_mfma_f32_16x16x32_bf16 v[24:27], v[148:151], v[104:107], v[24:27]
	v_mul_f32_e64 v36, v38, v36
	v_mul_f32_e64 v37, v39, v37
	v_pk_mul_f32 v[38:39], v[62:63], v[44:45]
	v_cvt_pk_bf16_f32 v36, v36, v37
	v_pk_mul_f32 v[38:39], v[40:41], v[38:39]
	v_mfma_f32_16x16x32_bf16 v[28:31], v[80:83], v[104:107], v[28:31]
	v_cvt_pk_bf16_f32 v37, v38, v39
	global_store_dwordx4 v[42:43], v[34:37], off
	v_mul_f32_e32 v38, 0xbfb8aa3b, v54
	v_mul_f32_e32 v39, 0xbfb8aa3b, v55
	v_mul_f32_e32 v35, 0xbfb8aa3b, v52
	v_exp_f32_e32 v36, v35
	v_mul_f32_e32 v35, 0xbfb8aa3b, v53
	v_exp_f32_e32 v37, v35
	v_exp_f32_e32 v38, v38
	v_exp_f32_e32 v39, v39
	v_add_f32_e32 v36, 1.0, v36
	v_add_f32_e32 v37, 1.0, v37
	v_rcp_f32_e32 v36, v36
	v_rcp_f32_e32 v37, v37
	v_add_f32_e32 v38, 1.0, v38
	v_add_f32_e32 v39, 1.0, v39
	v_rcp_f32_e32 v38, v38
	v_rcp_f32_e32 v39, v39
	v_pk_mul_f32 v[36:37], v[52:53], v[36:37]
	v_mfma_f32_16x16x32_bf16 v[20:23], v[88:91], v[76:79], v[20:23]
	v_mul_f32_e64 v24, v24, v36
	v_mul_f32_e64 v25, v25, v37
	v_pk_mul_f32 v[36:37], v[54:55], v[38:39]
	v_cvt_pk_bf16_f32 v24, v24, v25
	v_mul_f32_e32 v25, 0xbfb8aa3b, v28
	v_pk_mul_f32 v[26:27], v[26:27], v[36:37]
	v_exp_f32_e32 v36, v25
	v_mul_f32_e32 v25, 0xbfb8aa3b, v29
	v_exp_f32_e32 v37, v25
	v_cvt_pk_bf16_f32 v25, v26, v27
	v_add_f32_e32 v26, 1.0, v36
	v_mul_f32_e32 v36, 0xbfb8aa3b, v30
	v_add_f32_e32 v27, 1.0, v37
	v_mul_f32_e32 v37, 0xbfb8aa3b, v31
	v_exp_f32_e32 v36, v36
	v_exp_f32_e32 v37, v37
	v_mfma_f32_16x16x32_bf16 v[16:19], v[68:71], v[92:95], v[16:19]
	v_rcp_f32_e32 v26, v26
	v_rcp_f32_e32 v27, v27
	v_add_f32_e32 v36, 1.0, v36
	v_mfma_f32_16x16x32_bf16 v[20:23], v[152:155], v[104:107], v[20:23]
	v_add_f32_e32 v37, 1.0, v37
	v_rcp_f32_e32 v36, v36
	v_rcp_f32_e32 v37, v37
	v_mfma_f32_16x16x32_bf16 v[16:19], v[144:147], v[140:143], v[16:19]
	v_mul_f32_e64 v26, v28, v26
	v_mul_f32_e64 v27, v29, v27
	v_or_b32_e32 v34, 32, v2
	s_nop 0
	v_pk_mul_f32 v[20:21], v[20:21], v[26:27]
	v_or_b32_e32 v2, 48, v2
	v_cvt_pk_bf16_f32 v26, v20, v21
	v_pk_mul_f32 v[20:21], v[30:31], v[36:37]
	v_mad_i64_i32 v[34:35], s[2:3], v34, s24, v[32:33]
	v_pk_mul_f32 v[20:21], v[22:23], v[20:21]
	v_mfma_f32_16x16x32_bf16 v[12:15], v[72:75], v[92:95], v[12:15]
	v_cvt_pk_bf16_f32 v27, v20, v21
	v_mul_f32_e32 v20, 0xbfb8aa3b, v16
	v_exp_f32_e32 v22, v20
	v_mul_f32_e32 v20, 0xbfb8aa3b, v17
	v_exp_f32_e32 v23, v20
	v_mad_i64_i32 v[20:21], s[2:3], v2, s24, v[32:33]
	v_add_f32_e32 v2, 1.0, v22
	v_rcp_f32_e32 v22, v2
	v_add_f32_e32 v2, 1.0, v23
	v_mul_f32_e32 v23, 0xbfb8aa3b, v18
	global_store_dwordx4 v[34:35], v[24:27], off
	v_mfma_f32_16x16x32_bf16 v[8:11], v[84:87], v[92:95], v[8:11]
	s_nop 0
	v_exp_f32_e32 v24, v23
	v_mul_f32_e32 v23, 0xbfb8aa3b, v19
	v_exp_f32_e32 v25, v23
	v_rcp_f32_e32 v23, v2
	v_add_f32_e32 v2, 1.0, v24
	v_mfma_f32_16x16x32_bf16 v[12:15], v[148:151], v[140:143], v[12:15]
	v_rcp_f32_e32 v24, v2
	v_add_f32_e32 v2, 1.0, v25
	v_rcp_f32_e32 v25, v2
	v_mfma_f32_16x16x32_bf16 v[8:11], v[80:83], v[140:143], v[8:11]
	v_mul_f32_e64 v16, v16, v22
	v_mul_f32_e64 v17, v17, v23
	s_nop 1
	v_pk_mul_f32 v[12:13], v[12:13], v[16:17]
	v_pk_mul_f32 v[16:17], v[18:19], v[24:25]
	v_cvt_pk_bf16_f32 v12, v12, v13
	s_nop 0
	v_mul_f32_e32 v2, 0xbfb8aa3b, v8
	v_exp_f32_e32 v2, v2
	v_mul_f32_e32 v13, 0xbfb8aa3b, v9
	v_pk_mul_f32 v[14:15], v[14:15], v[16:17]
	v_exp_f32_e32 v16, v13
	v_cvt_pk_bf16_f32 v13, v14, v15
	v_add_f32_e32 v2, 1.0, v2
	v_mul_f32_e32 v15, 0xbfb8aa3b, v10
	v_rcp_f32_e32 v14, v2
	v_add_f32_e32 v2, 1.0, v16
	v_exp_f32_e32 v16, v15
	v_mul_f32_e32 v15, 0xbfb8aa3b, v11
	v_mfma_f32_16x16x32_bf16 v[4:7], v[88:91], v[92:95], v[4:7]
	v_exp_f32_e32 v17, v15
	v_rcp_f32_e32 v15, v2
	v_add_f32_e32 v2, 1.0, v16
	v_mfma_f32_16x16x32_bf16 v[4:7], v[152:155], v[140:143], v[4:7]
	v_rcp_f32_e32 v16, v2
	v_add_f32_e32 v2, 1.0, v17
	v_rcp_f32_e32 v17, v2
	v_pk_mul_f32 v[8:9], v[8:9], v[14:15]
	s_nop 3
	v_pk_mul_f32 v[4:5], v[4:5], v[8:9]
	s_nop 0
	v_cvt_pk_bf16_f32 v14, v4, v5
	v_pk_mul_f32 v[4:5], v[10:11], v[16:17]
	s_nop 0
	v_pk_mul_f32 v[4:5], v[6:7], v[4:5]
	s_nop 0
	v_cvt_pk_bf16_f32 v15, v4, v5
	global_store_dwordx4 v[20:21], v[12:15], off
	s_cbranch_scc0 .LBB0_110

; template <int EPI>
; __device__ __forceinline__ void gemm_tile(const bf16_t* __restrict__ A, const int lda, const bf16_t* __restrict__ Bt, const int ldb,
;                                           const int K, const int m0, const int n0, void* Cout, const int ldc, char* lds, const int tid) {
;     ...
;   f32x4 acc[4][4];
; #pragma unroll
;   for (int m = 0; m < 4; ++m)
; #pragma unroll
;     for (int n = 0; n < 4; ++n) acc[m][n] = (f32x4){0.f, 0.f, 0.f, 0.f};
;   const int nt = K >> 6;
;   const int st_row = tid >> 3, st_c = (tid & 7) ^ ((tid >> 4) & 7);
;   auto stageA = [&](int kt, int buf) {
; #pragma unroll
;     for (int i = 0; i < 4; ++i) {
;       const int off = tid * 16 + i * 4096, r = st_row + i * 32;
;       const bf16_t* ga = A + (size_t)(m0 + r) * lda + kt * 64 + st_c * 8;
;       __builtin_amdgcn_global_load_lds((const unsigned*)ga, (__attribute__((address_space(3))) unsigned*)(lds + buf * 32768 + off), 16, 0, 0);
;     }
;   };
;   auto stageB = [&](int kt, int buf) {
; #pragma unroll
;     for (int i = 0; i < 4; ++i) {
;       const int off = tid * 16 + i * 4096, r = st_row + i * 32;
;       const bf16_t* gb = Bt + (size_t)(n0 + r) * ldb + kt * 64 + st_c * 8;
;       __builtin_amdgcn_global_load_lds((const unsigned*)gb, (__attribute__((address_space(3))) unsigned*)(lds + buf * 32768 + 16384 + off), 16, 0, 0);
;     }
;   };
;   auto stage = [&](int kt, int buf) { stageA(kt, buf); stageB(kt, buf); };
;   const int fsw = (fr >> 1) & 7;
;   const int xk0 = (fq ^ fsw) << 4, xk1 = ((4 + fq) ^ fsw) << 4;
;   stage(0, 0);
; template <int EPI>
; __device__ __forceinline__ void gemm_phase(const bf16_t* A, int lda, const bf16_t* Bt, int ldb, int K, int ntn, void* C, int ldc, char* lds, int bid, int nb, const int tid) {
;   constexpr int GM = 4, nM = MT / 128;
;   const int ntiles = nM * ntn, nig = GM * ntn;
;   const int pos = (EPI != EPI_SWIGLU && (nb & 7) == 0) ? (bid & 7) * (nb >> 3) + (bid >> 3) : bid;
;   for (int L = pos; L < ntiles; L += nb) {
;     int mt, nn;
;     if (EPI == EPI_SWIGLU) { mt = L / ntn; nn = L % ntn; }
;     else { const int gid = L / nig, fm = gid * GM, gsz = min(nM - fm, GM), rem = L - gid * nig; mt = fm + rem % gsz; nn = rem / gsz; }
;     gemm_tile<EPI>(A, lda, Bt, ldb, K, mt * 128, nn * 128, C, ldc, lds, tid);
.LBB0_124:
	s_ashr_i32 s2, s24, 31
	s_lshr_b32 s2, s2, 27
	s_add_i32 s2, s24, s2
	s_ashr_i32 s3, s2, 5
	s_lshl_b32 s3, s3, 2
	s_sub_i32 s23, 0x85, s3
	s_min_u32 s23, s23, 4
	v_cvt_f32_ubyte0_e32 v4, s23
	v_rcp_iflag_f32_e32 v4, v4
	s_sub_i32 s27, 0, s23
	s_andn2_b32 s2, s2, 31
	s_sub_i32 s2, s24, s2
	v_mul_f32_e32 v4, 0x4f7ffffe, v4
	v_cvt_u32_f32_e32 v4, v4
	s_abs_i32 s26, s2
	s_ashr_i32 s25, s2, 31
	v_add_u32_e32 v10, 0x1000, v176
	v_readfirstlane_b32 s29, v4
	s_mul_i32 s27, s27, s29
	s_mul_hi_u32 s27, s29, s27
	s_add_i32 s29, s29, s27
	s_mul_hi_u32 s27, s26, s29
	s_mul_i32 s29, s27, s23
	s_sub_i32 s26, s26, s29
	s_add_i32 s34, s27, 1
	s_sub_i32 s29, s26, s23
	s_cmp_ge_u32 s26, s23
	s_cselect_b32 s27, s34, s27
	s_cselect_b32 s26, s29, s26
	s_add_i32 s29, s27, 1
	s_cmp_ge_u32 s26, s23
	s_cselect_b32 s26, s29, s27
	s_xor_b32 s26, s26, s25
	s_sub_i32 s25, s26, s25
	s_mul_i32 s23, s25, s23
	s_sub_i32 s2, s2, s23
	s_add_i32 s3, s3, s2
	s_lshl_b32 s3, s3, 7
	v_add_u32_e32 v4, s3, v131
	v_ashrrev_i32_e32 v5, 31, v4
	v_lshlrev_b64 v[4:5], 11, v[4:5]
	v_readfirstlane_b32 s23, v176
	v_lshl_add_u64 v[6:7], v[0:1], 0, v[4:5]
	s_mov_b32 m0, s23
	v_readfirstlane_b32 s23, v10
	global_load_lds_dwordx4 v[6:7], off
	v_add_u32_e32 v6, s3, v177
	v_ashrrev_i32_e32 v7, 31, v6
	v_lshlrev_b64 v[6:7], 11, v[6:7]
	v_lshl_add_u64 v[8:9], v[0:1], 0, v[6:7]
	s_mov_b32 m0, s23
	v_add_u32_e32 v12, 0x2000, v176
	global_load_lds_dwordx4 v[8:9], off
	v_add_u32_e32 v8, s3, v178
	v_ashrrev_i32_e32 v9, 31, v8
	v_lshlrev_b64 v[8:9], 11, v[8:9]
	v_readfirstlane_b32 s23, v12
	v_lshl_add_u64 v[10:11], v[0:1], 0, v[8:9]
	s_mov_b32 m0, s23
	v_add_u32_e32 v14, 0x3000, v176
	global_load_lds_dwordx4 v[10:11], off
	v_add_u32_e32 v10, s3, v179
	v_ashrrev_i32_e32 v11, 31, v10
	v_lshlrev_b64 v[10:11], 11, v[10:11]
	v_readfirstlane_b32 s23, v14
	s_lshl_b32 s2, s25, 7
	v_lshl_add_u64 v[12:13], v[0:1], 0, v[10:11]
	s_mov_b32 m0, s23
	v_add_u32_e32 v16, 0x4000, v176
	global_load_lds_dwordx4 v[12:13], off
	v_add_u32_e32 v12, s2, v131
	v_ashrrev_i32_e32 v13, 31, v12
	v_lshlrev_b64 v[12:13], 11, v[12:13]
	v_readfirstlane_b32 s23, v16
	v_lshl_add_u64 v[14:15], v[132:133], 0, v[12:13]
	s_mov_b32 m0, s23
	v_add_u32_e32 v18, 0x5000, v176
	global_load_lds_dwordx4 v[14:15], off
	v_add_u32_e32 v14, s2, v177
	v_ashrrev_i32_e32 v15, 31, v14
	v_lshlrev_b64 v[14:15], 11, v[14:15]
	v_readfirstlane_b32 s23, v18
	v_lshl_add_u64 v[16:17], v[132:133], 0, v[14:15]
	s_mov_b32 m0, s23
	v_add_u32_e32 v20, 0x6000, v176
	global_load_lds_dwordx4 v[16:17], off
	v_add_u32_e32 v16, s2, v178
	v_ashrrev_i32_e32 v17, 31, v16
	v_lshlrev_b64 v[16:17], 11, v[16:17]
	v_readfirstlane_b32 s23, v20
	v_lshl_add_u64 v[18:19], v[132:133], 0, v[16:17]
	s_mov_b32 m0, s23
	v_add_u32_e32 v22, 0x7000, v176
	global_load_lds_dwordx4 v[18:19], off
	v_add_u32_e32 v18, s2, v179
	v_ashrrev_i32_e32 v19, 31, v18
	v_lshlrev_b64 v[18:19], 11, v[18:19]
	v_readfirstlane_b32 s23, v22
	v_lshl_add_u64 v[20:21], v[132:133], 0, v[18:19]
	s_mov_b32 m0, s23
	v_lshl_add_u64 v[148:149], v[136:137], 0, v[4:5]
	global_load_lds_dwordx4 v[20:21], off
	v_mov_b32_e32 v4, 0
	s_mov_b32 s26, 0
	v_lshl_add_u64 v[140:141], v[134:135], 0, v[12:13]
	v_lshl_add_u64 v[142:143], v[134:135], 0, v[14:15]
	v_lshl_add_u64 v[144:145], v[134:135], 0, v[16:17]
	v_lshl_add_u64 v[146:147], v[134:135], 0, v[18:19]
	v_lshl_add_u64 v[150:151], v[136:137], 0, v[6:7]
	v_lshl_add_u64 v[152:153], v[136:137], 0, v[8:9]
	v_lshl_add_u64 v[154:155], v[136:137], 0, v[10:11]
	s_mov_b64 s[34:35], 0
	v_mov_b32_e32 v5, v4
	v_mov_b32_e32 v6, v4
	v_mov_b32_e32 v7, v4
	v_mov_b32_e32 v12, v4
	v_mov_b32_e32 v13, v4
	v_mov_b32_e32 v14, v4
	v_mov_b32_e32 v15, v4
	s_waitcnt vmcnt(0)
	v_mov_b32_e32 v40, v4
	v_mov_b32_e32 v41, v4
	v_mov_b32_e32 v42, v4
	v_mov_b32_e32 v43, v4
	v_mov_b32_e32 v44, v4
	v_mov_b32_e32 v45, v4
	v_mov_b32_e32 v46, v4
	v_mov_b32_e32 v47, v4
	v_mov_b32_e32 v48, v4
	v_mov_b32_e32 v49, v4
	v_mov_b32_e32 v50, v4
	v_mov_b32_e32 v51, v4
	v_mov_b32_e32 v32, v4
	v_mov_b32_e32 v33, v4
	v_mov_b32_e32 v34, v4
	v_mov_b32_e32 v35, v4
	v_mov_b32_e32 v16, v4
	v_mov_b32_e32 v17, v4
	v_mov_b32_e32 v18, v4
	v_mov_b32_e32 v19, v4
	v_mov_b32_e32 v8, v4
	v_mov_b32_e32 v9, v4
	v_mov_b32_e32 v10, v4
	v_mov_b32_e32 v11, v4
	v_mov_b32_e32 v24, v4
	v_mov_b32_e32 v25, v4
	v_mov_b32_e32 v26, v4
	v_mov_b32_e32 v27, v4
	v_mov_b32_e32 v20, v4
	v_mov_b32_e32 v21, v4
	v_mov_b32_e32 v22, v4
	v_mov_b32_e32 v23, v4
	v_mov_b32_e32 v28, v4
	v_mov_b32_e32 v29, v4
	v_mov_b32_e32 v30, v4
	v_mov_b32_e32 v31, v4
	v_mov_b32_e32 v36, v4
	v_mov_b32_e32 v37, v4
	v_mov_b32_e32 v38, v4
	v_mov_b32_e32 v39, v4
	v_mov_b32_e32 v52, v4
	v_mov_b32_e32 v53, v4
	v_mov_b32_e32 v54, v4
	v_mov_b32_e32 v55, v4
	v_mov_b32_e32 v56, v4
	v_mov_b32_e32 v57, v4
	v_mov_b32_e32 v58, v4
	v_mov_b32_e32 v59, v4
	v_mov_b32_e32 v60, v4
	v_mov_b32_e32 v61, v4
	v_mov_b32_e32 v62, v4
	v_mov_b32_e32 v63, v4
	v_mov_b32_e32 v64, v4
	v_mov_b32_e32 v65, v4
	v_mov_b32_e32 v66, v4
	v_mov_b32_e32 v67, v4
	s_waitcnt vmcnt(0)
	s_barrier
	v_readfirstlane_b32 s100, v176
	s_add_i32 m0, s100, 0xc000
	v_lshl_add_u64 v[226:227], v[140:141], 0, s[34:35]
	global_load_lds_dwordx4 v[226:227], off
	s_add_i32 m0, s100, 0xd000
	v_lshl_add_u64 v[226:227], v[142:143], 0, s[34:35]
	global_load_lds_dwordx4 v[226:227], off
	s_add_i32 m0, s100, 0xe000
	v_lshl_add_u64 v[226:227], v[144:145], 0, s[34:35]
	global_load_lds_dwordx4 v[226:227], off
	s_add_i32 m0, s100, 0xf000
	v_lshl_add_u64 v[226:227], v[146:147], 0, s[34:35]
	global_load_lds_dwordx4 v[226:227], off
	s_add_i32 m0, s100, 0x8000
	v_lshl_add_u64 v[226:227], v[148:149], 0, s[34:35]
	global_load_lds_dwordx4 v[226:227], off
	s_add_i32 m0, s100, 0x9000
	v_lshl_add_u64 v[226:227], v[150:151], 0, s[34:35]
	global_load_lds_dwordx4 v[226:227], off
	s_add_i32 m0, s100, 0xa000
	v_lshl_add_u64 v[226:227], v[152:153], 0, s[34:35]
	global_load_lds_dwordx4 v[226:227], off
	s_add_i32 m0, s100, 0xb000
	v_lshl_add_u64 v[226:227], v[154:155], 0, s[34:35]
	global_load_lds_dwordx4 v[226:227], off
	v_add_u32_e32 v218, v174, v181
	v_add_u32_e32 v220, v174, v180
	ds_read_b128 v[104:107], v218
	ds_read_b128 v[100:103], v218 offset:2048
	ds_read_b128 v[96:99], v218 offset:4096
	ds_read_b128 v[84:87], v218 offset:6144
	ds_read_b128 v[184:187], v220 offset:16384
	ds_read_b128 v[188:191], v220 offset:18432
	ds_read_b128 v[192:195], v220 offset:20480
	ds_read_b128 v[196:199], v220 offset:22528
; template <int EPI>
; __device__ __forceinline__ void gemm_tile(const bf16_t* __restrict__ A, const int lda, const bf16_t* __restrict__ Bt, const int ldb,
;                                           const int K, const int m0, const int n0, void* Cout, const int ldc, char* lds, const int tid) {
;     ...
;   for (int kt = 0; kt < nt; ++kt) {
;     asm volatile("s_waitcnt vmcnt(0)" ::: "memory");
;     __syncthreads();
;     if (kt + 1 < nt) stageB(kt + 1, (kt + 1) & 1);
;     const char* sa = lds + (kt & 1) * 32768;
;     const char* sb = sa + 16384;
;     bf16x8 af[2][4], bfr[2][4];
; #pragma unroll
;     for (int ks = 0; ks < 2; ++ks) {
; #pragma unroll
;       for (int m = 0; m < 4; ++m) af[ks][m] = *(const bf16x8*)(sa + (wr * 64 + m * 16 + fr) * 128 + (ks ? xk1 : xk0));
; #pragma unroll
;       for (int n = 0; n < 4; ++n) bfr[ks][n] = *(const bf16x8*)(sb + (wc * 64 + n * 16 + fr) * 128 + (ks ? xk1 : xk0));
;     }
;     if (kt + 1 < nt) stageA(kt + 1, (kt + 1) & 1);
; #pragma unroll
;     for (int ks = 0; ks < 2; ++ks)
; #pragma unroll
;       for (int m = 0; m < 4; ++m)
; #pragma unroll
;         for (int n = 0; n < 4; ++n) acc[m][n] = __builtin_amdgcn_mfma_f32_16x16x32_bf16(bfr[ks][n], af[ks][m], acc[m][n], 0, 0, 0);
;   }
.LBB0_125:
	s_add_i32 s25, s26, 0x8000
	s_and_b32 s23, s25, 0x8000
	s_and_b32 s26, s26, 0x8000
	s_waitcnt lgkmcnt(0)
	v_mfma_f32_16x16x32_bf16 v[64:67], v[184:187], v[104:107], v[64:67]
	v_or_b32_e32 v216, s26, v175
	v_add_u32_e32 v222, v216, v181
	v_mfma_f32_16x16x32_bf16 v[60:63], v[188:191], v[104:107], v[60:63]
	v_add_u32_e32 v224, v216, v180
	ds_read_b128 v[200:203], v222
	v_mfma_f32_16x16x32_bf16 v[56:59], v[192:195], v[104:107], v[56:59]
	ds_read_b128 v[204:207], v222 offset:2048
	ds_read_b128 v[92:95], v222 offset:4096
	v_mfma_f32_16x16x32_bf16 v[52:55], v[196:199], v[104:107], v[52:55]
	ds_read_b128 v[68:71], v222 offset:6144
	ds_read_b128 v[88:91], v224 offset:16384
	v_mfma_f32_16x16x32_bf16 v[36:39], v[184:187], v[100:103], v[36:39]
	ds_read_b128 v[80:83], v224 offset:18432
	ds_read_b128 v[72:75], v224 offset:20480
	v_mfma_f32_16x16x32_bf16 v[28:31], v[188:191], v[100:103], v[28:31]
	ds_read_b128 v[76:79], v224 offset:22528
	v_or_b32_e32 v214, s23, v174
	v_mfma_f32_16x16x32_bf16 v[20:23], v[192:195], v[100:103], v[20:23]
	v_add_u32_e32 v218, v214, v181
	v_add_u32_e32 v220, v214, v180
	v_mfma_f32_16x16x32_bf16 v[24:27], v[196:199], v[100:103], v[24:27]
	v_readfirstlane_b32 s100, v176
	s_add_i32 s100, s100, s26
	v_mfma_f32_16x16x32_bf16 v[8:11], v[184:187], v[96:99], v[8:11]
	s_add_u32 s62, s34, 0x80
	s_addc_u32 s63, s35, 0
	v_mfma_f32_16x16x32_bf16 v[16:19], v[188:191], v[96:99], v[16:19]
	v_mfma_f32_16x16x32_bf16 v[32:35], v[192:195], v[96:99], v[32:35]
	v_mfma_f32_16x16x32_bf16 v[48:51], v[196:199], v[96:99], v[48:51]
	v_mfma_f32_16x16x32_bf16 v[44:47], v[184:187], v[84:87], v[44:47]
	v_mfma_f32_16x16x32_bf16 v[40:43], v[188:191], v[84:87], v[40:43]
	v_mfma_f32_16x16x32_bf16 v[12:15], v[192:195], v[84:87], v[12:15]
	v_mfma_f32_16x16x32_bf16 v[4:7], v[196:199], v[84:87], v[4:7]
	s_waitcnt vmcnt(0) lgkmcnt(0)
	s_barrier
	s_cmpk_eq_i32 s34, 0x700
	s_cbranch_scc1 .Lr_last_125
	v_mfma_f32_16x16x32_bf16 v[64:67], v[88:91], v[200:203], v[64:67]
	s_add_i32 m0, s100, 0x4000
	v_lshl_add_u64 v[226:227], v[140:141], 0, s[62:63]
	global_load_lds_dwordx4 v[226:227], off
	v_mfma_f32_16x16x32_bf16 v[60:63], v[80:83], v[200:203], v[60:63]
	s_add_i32 m0, s100, 0x5000
	v_lshl_add_u64 v[226:227], v[142:143], 0, s[62:63]
	global_load_lds_dwordx4 v[226:227], off
	v_mfma_f32_16x16x32_bf16 v[56:59], v[72:75], v[200:203], v[56:59]
	s_add_i32 m0, s100, 0x6000
	v_lshl_add_u64 v[226:227], v[144:145], 0, s[62:63]
	global_load_lds_dwordx4 v[226:227], off
	v_mfma_f32_16x16x32_bf16 v[52:55], v[76:79], v[200:203], v[52:55]
	s_add_i32 m0, s100, 0x7000
	v_lshl_add_u64 v[226:227], v[146:147], 0, s[62:63]
	global_load_lds_dwordx4 v[226:227], off
	v_mfma_f32_16x16x32_bf16 v[36:39], v[88:91], v[204:207], v[36:39]
	s_mov_b32 m0, s100
	v_lshl_add_u64 v[226:227], v[148:149], 0, s[62:63]
	global_load_lds_dwordx4 v[226:227], off
	v_mfma_f32_16x16x32_bf16 v[28:31], v[80:83], v[204:207], v[28:31]
	s_add_i32 m0, s100, 0x1000
	v_lshl_add_u64 v[226:227], v[150:151], 0, s[62:63]
	global_load_lds_dwordx4 v[226:227], off
	v_mfma_f32_16x16x32_bf16 v[20:23], v[72:75], v[204:207], v[20:23]
	s_add_i32 m0, s100, 0x2000
	v_lshl_add_u64 v[226:227], v[152:153], 0, s[62:63]
	global_load_lds_dwordx4 v[226:227], off
	v_mfma_f32_16x16x32_bf16 v[24:27], v[76:79], v[204:207], v[24:27]
	s_add_i32 m0, s100, 0x3000
	v_lshl_add_u64 v[226:227], v[154:155], 0, s[62:63]
	global_load_lds_dwordx4 v[226:227], off
	v_mfma_f32_16x16x32_bf16 v[8:11], v[88:91], v[92:95], v[8:11]
	ds_read_b128 v[104:107], v218
	v_mfma_f32_16x16x32_bf16 v[16:19], v[80:83], v[92:95], v[16:19]
	ds_read_b128 v[100:103], v218 offset:2048
	v_mfma_f32_16x16x32_bf16 v[32:35], v[72:75], v[92:95], v[32:35]
	ds_read_b128 v[96:99], v218 offset:4096
	v_mfma_f32_16x16x32_bf16 v[48:51], v[76:79], v[92:95], v[48:51]
	ds_read_b128 v[84:87], v218 offset:6144
	v_mfma_f32_16x16x32_bf16 v[44:47], v[88:91], v[68:71], v[44:47]
	ds_read_b128 v[184:187], v220 offset:16384
	v_mfma_f32_16x16x32_bf16 v[40:43], v[80:83], v[68:71], v[40:43]
	ds_read_b128 v[188:191], v220 offset:18432
	v_mfma_f32_16x16x32_bf16 v[12:15], v[72:75], v[68:71], v[12:15]
	ds_read_b128 v[192:195], v220 offset:20480
	v_mfma_f32_16x16x32_bf16 v[4:7], v[76:79], v[68:71], v[4:7]
	ds_read_b128 v[196:199], v220 offset:22528
	s_add_u32 s34, s34, 0x80
	s_addc_u32 s35, s35, 0
	s_mov_b32 s26, s25
	s_branch .LBB0_125
.Lr_last_125:
	v_mfma_f32_16x16x32_bf16 v[64:67], v[88:91], v[200:203], v[64:67]
	v_mfma_f32_16x16x32_bf16 v[60:63], v[80:83], v[200:203], v[60:63]
	v_mfma_f32_16x16x32_bf16 v[56:59], v[72:75], v[200:203], v[56:59]
	v_mfma_f32_16x16x32_bf16 v[52:55], v[76:79], v[200:203], v[52:55]
	v_mfma_f32_16x16x32_bf16 v[36:39], v[88:91], v[204:207], v[36:39]
	v_mfma_f32_16x16x32_bf16 v[28:31], v[80:83], v[204:207], v[28:31]
	v_mfma_f32_16x16x32_bf16 v[20:23], v[72:75], v[204:207], v[20:23]
	v_mfma_f32_16x16x32_bf16 v[24:27], v[76:79], v[204:207], v[24:27]
	v_mfma_f32_16x16x32_bf16 v[8:11], v[88:91], v[92:95], v[8:11]
	v_mfma_f32_16x16x32_bf16 v[16:19], v[80:83], v[92:95], v[16:19]
	v_mfma_f32_16x16x32_bf16 v[32:35], v[72:75], v[92:95], v[32:35]
	v_mfma_f32_16x16x32_bf16 v[48:51], v[76:79], v[92:95], v[48:51]
	v_mfma_f32_16x16x32_bf16 v[44:47], v[88:91], v[68:71], v[44:47]
	v_mfma_f32_16x16x32_bf16 v[40:43], v[80:83], v[68:71], v[40:43]
	v_mfma_f32_16x16x32_bf16 v[12:15], v[72:75], v[68:71], v[12:15]
	v_mfma_f32_16x16x32_bf16 v[4:7], v[76:79], v[68:71], v[4:7]
	s_add_u32 s34, s34, 0x80
	s_addc_u32 s35, s35, 0
	s_mov_b32 s26, s25
	v_add_u32_e32 v84, s23, v174
	v_add_u32_e32 v80, v84, v181
	s_waitcnt vmcnt(0)
	s_waitcnt vmcnt(0) lgkmcnt(0)
	s_barrier
	ds_read_b128 v[68:71], v80
	ds_read_b128 v[72:75], v80 offset:2048
	ds_read_b128 v[76:79], v80 offset:4096
	ds_read_b128 v[80:83], v80 offset:6144
	v_add_u32_e32 v96, v84, v180
	ds_read_b128 v[84:87], v96 offset:16384
	ds_read_b128 v[88:91], v96 offset:18432
	ds_read_b128 v[92:95], v96 offset:20480
	ds_read_b128 v[96:99], v96 offset:22528
	v_add_u32_e32 v139, s23, v175
	v_add_u32_e32 v144, v139, v181
	s_waitcnt lgkmcnt(3)
	v_mfma_f32_16x16x32_bf16 v[36:39], v[84:87], v[72:75], v[36:39]
	ds_read_b128 v[100:103], v144
	ds_read_b128 v[104:107], v144 offset:2048
	ds_read_b128 v[140:143], v144 offset:4096
	ds_read_b128 v[144:147], v144 offset:6144
	v_add_u32_e32 v139, v139, v180
	ds_read_b128 v[148:151], v139 offset:16384
	ds_read_b128 v[152:155], v139 offset:18432
	ds_read_b128 v[184:187], v139 offset:20480
	ds_read_b128 v[188:191], v139 offset:22528
	v_mfma_f32_16x16x32_bf16 v[64:67], v[84:87], v[68:71], v[64:67]
	v_readlane_b32 s26, v253, 25
	v_readlane_b32 s27, v253, 26
	v_mov_b32_e32 v139, v3
	s_waitcnt lgkmcnt(10)
	v_mfma_f32_16x16x32_bf16 v[60:63], v[88:91], v[68:71], v[60:63]
	s_add_i32 s24, s24, s0
	s_cmpk_lg_i32 s0, 0x200
	s_cbranch_scc1 .Ltail_skip_2
	s_cmpk_lt_i32 s24, 0x400
	s_cbranch_scc1 .Ltail_skip_2
	s_cmpk_ge_i32 s24, 0x600
	s_cbranch_scc1 .Ltail_skip_2
	v_readlane_b32 s24, v254, 61
	s_nop 3
	s_addk_i32 s24, 0x400

; template <int EPI>
; __device__ __forceinline__ void gemm_tile(const bf16_t* __restrict__ A, const int lda, const bf16_t* __restrict__ Bt, const int ldb,
;                                           const int K, const int m0, const int n0, void* Cout, const int ldc, char* lds, const int tid) {
;     ...
;   f32x4 acc[4][4];
; #pragma unroll
;   for (int m = 0; m < 4; ++m)
; #pragma unroll
;     for (int n = 0; n < 4; ++n) acc[m][n] = (f32x4){0.f, 0.f, 0.f, 0.f};
;   const int nt = K >> 6;
;   const int st_row = tid >> 3, st_c = (tid & 7) ^ ((tid >> 4) & 7);
;   auto stageA = [&](int kt, int buf) {
; #pragma unroll
;     for (int i = 0; i < 4; ++i) {
;       const int off = tid * 16 + i * 4096, r = st_row + i * 32;
;       const bf16_t* ga = A + (size_t)(m0 + r) * lda + kt * 64 + st_c * 8;
;       __builtin_amdgcn_global_load_lds((const unsigned*)ga, (__attribute__((address_space(3))) unsigned*)(lds + buf * 32768 + off), 16, 0, 0);
;     }
;   };
;   auto stageB = [&](int kt, int buf) {
; #pragma unroll
;     for (int i = 0; i < 4; ++i) {
;       const int off = tid * 16 + i * 4096, r = st_row + i * 32;
;       const bf16_t* gb = Bt + (size_t)(n0 + r) * ldb + kt * 64 + st_c * 8;
;       __builtin_amdgcn_global_load_lds((const unsigned*)gb, (__attribute__((address_space(3))) unsigned*)(lds + buf * 32768 + 16384 + off), 16, 0, 0);
;     }
;   };
;   auto stage = [&](int kt, int buf) { stageA(kt, buf); stageB(kt, buf); };
;   const int fsw = (fr >> 1) & 7;
;   const int xk0 = (fq ^ fsw) << 4, xk1 = ((4 + fq) ^ fsw) << 4;
;   stage(0, 0);
;   for (int kt = 0; kt < nt; ++kt) {
;     asm volatile("s_waitcnt vmcnt(0)" ::: "memory");
;     __syncthreads();
; template <int EPI>
; __device__ __forceinline__ void gemm_phase(const bf16_t* A, int lda, const bf16_t* Bt, int ldb, int K, int ntn, void* C, int ldc, char* lds, int bid, int nb, const int tid) {
;     ...
;   const int ntiles = nM * ntn, nig = GM * ntn;
;   const int pos = (EPI != EPI_SWIGLU && (nb & 7) == 0) ? (bid & 7) * (nb >> 3) + (bid >> 3) : bid;
;   for (int L = pos; L < ntiles; L += nb) {
;     int mt, nn;
;     if (EPI == EPI_SWIGLU) { mt = L / ntn; nn = L % ntn; }
;     else { const int gid = L / nig, fm = gid * GM, gsz = min(nM - fm, GM), rem = L - gid * nig; mt = fm + rem % gsz; nn = rem / gsz; }
;     gemm_tile<EPI>(A, lda, Bt, ldb, K, mt * 128, nn * 128, C, ldc, lds, tid);
.LBB0_648:
	s_mul_hi_i32 s2, s23, 0x84210843
	s_add_i32 s2, s2, s23
	s_lshr_b32 s3, s2, 31
	s_ashr_i32 s2, s2, 6
	s_add_i32 s2, s2, s3
	s_lshl_b32 s3, s2, 2
	s_sub_i32 s24, 0x85, s3
	s_min_u32 s24, s24, 4
	v_cvt_f32_ubyte0_e32 v2, s24
	v_rcp_iflag_f32_e32 v2, v2
	s_sub_i32 s27, 0, s24
	s_mulk_i32 s2, 0xff84
	s_add_i32 s2, s2, s23
	v_mul_f32_e32 v2, 0x4f7ffffe, v2
	v_cvt_u32_f32_e32 v2, v2
	s_abs_i32 s26, s2
	s_ashr_i32 s25, s2, 31
	v_readfirstlane_b32 s29, v2
	s_mul_i32 s27, s27, s29
	s_mul_hi_u32 s27, s29, s27
	s_add_i32 s29, s29, s27
	s_mul_hi_u32 s27, s26, s29
	s_mul_i32 s29, s27, s24
	s_sub_i32 s26, s26, s29
	s_add_i32 s29, s27, 1
	s_sub_i32 s34, s26, s24
	s_cmp_ge_u32 s26, s24
	s_cselect_b32 s27, s29, s27
	s_cselect_b32 s26, s34, s26
	s_add_i32 s29, s27, 1
	s_cmp_ge_u32 s26, s24
	s_cselect_b32 s26, s29, s27
	s_xor_b32 s26, s26, s25
	s_sub_i32 s25, s26, s25
	s_mul_i32 s24, s25, s24
	s_sub_i32 s2, s2, s24
	s_add_i32 s3, s3, s2
	s_lshl_b32 s3, s3, 7
	v_add_u32_e32 v4, s3, v174
	v_ashrrev_i32_e32 v5, 31, v4
	v_lshlrev_b64 v[4:5], 11, v[4:5]
	v_readfirstlane_b32 s24, v177
	v_lshl_add_u64 v[6:7], v[0:1], 0, v[4:5]
	s_mov_b32 m0, s24
	v_add_u32_e32 v2, 0x1000, v177
	global_load_lds_dwordx4 v[6:7], off
	v_add_u32_e32 v6, s3, v178
	v_ashrrev_i32_e32 v7, 31, v6
	v_lshlrev_b64 v[6:7], 11, v[6:7]
	v_readfirstlane_b32 s24, v2
	v_lshl_add_u64 v[8:9], v[0:1], 0, v[6:7]
	s_mov_b32 m0, s24
	v_add_u32_e32 v2, 0x2000, v177
	global_load_lds_dwordx4 v[8:9], off
	v_add_u32_e32 v8, s3, v179
	v_ashrrev_i32_e32 v9, 31, v8
	v_lshlrev_b64 v[8:9], 11, v[8:9]
	v_readfirstlane_b32 s24, v2
	v_lshl_add_u64 v[10:11], v[0:1], 0, v[8:9]
	s_mov_b32 m0, s24
	v_add_u32_e32 v2, 0x3000, v177
	global_load_lds_dwordx4 v[10:11], off
	v_add_u32_e32 v10, s3, v180
	v_ashrrev_i32_e32 v11, 31, v10
	v_lshlrev_b64 v[10:11], 11, v[10:11]
	v_readfirstlane_b32 s24, v2
	s_lshl_b32 s2, s25, 7
	v_lshl_add_u64 v[12:13], v[0:1], 0, v[10:11]
	s_mov_b32 m0, s24
	v_add_u32_e32 v2, 0x4000, v177
	global_load_lds_dwordx4 v[12:13], off
	v_add_u32_e32 v12, s2, v174
	v_ashrrev_i32_e32 v13, 31, v12
	v_lshlrev_b64 v[12:13], 11, v[12:13]
	v_readfirstlane_b32 s24, v2
	v_lshl_add_u64 v[14:15], v[132:133], 0, v[12:13]
	s_mov_b32 m0, s24
	v_add_u32_e32 v2, 0x5000, v177
	global_load_lds_dwordx4 v[14:15], off
	v_add_u32_e32 v14, s2, v178
	v_ashrrev_i32_e32 v15, 31, v14
	v_lshlrev_b64 v[14:15], 11, v[14:15]
	v_readfirstlane_b32 s24, v2
	v_lshl_add_u64 v[16:17], v[132:133], 0, v[14:15]
	s_mov_b32 m0, s24
	v_add_u32_e32 v2, 0x6000, v177
	global_load_lds_dwordx4 v[16:17], off
	v_add_u32_e32 v16, s2, v179
	v_ashrrev_i32_e32 v17, 31, v16
	v_lshlrev_b64 v[16:17], 11, v[16:17]
	v_readfirstlane_b32 s24, v2
	v_lshl_add_u64 v[18:19], v[132:133], 0, v[16:17]
	s_mov_b32 m0, s24
	v_add_u32_e32 v2, 0x7000, v177
	global_load_lds_dwordx4 v[18:19], off
	v_add_u32_e32 v18, s2, v180
	v_ashrrev_i32_e32 v19, 31, v18
	v_lshlrev_b64 v[18:19], 11, v[18:19]
	v_readfirstlane_b32 s24, v2
	v_lshl_add_u64 v[20:21], v[132:133], 0, v[18:19]
	s_mov_b32 m0, s24
	v_lshl_add_u64 v[148:149], v[138:139], 0, v[4:5]
	global_load_lds_dwordx4 v[20:21], off
	v_mov_b32_e32 v4, 0
	s_mov_b32 s25, 0
	v_lshl_add_u64 v[140:141], v[136:137], 0, v[12:13]
	v_lshl_add_u64 v[142:143], v[136:137], 0, v[14:15]
	v_lshl_add_u64 v[144:145], v[136:137], 0, v[16:17]
	v_lshl_add_u64 v[146:147], v[136:137], 0, v[18:19]
	v_lshl_add_u64 v[150:151], v[138:139], 0, v[6:7]
	v_lshl_add_u64 v[152:153], v[138:139], 0, v[8:9]
	v_lshl_add_u64 v[154:155], v[138:139], 0, v[10:11]
	s_mov_b64 s[34:35], 0
	v_mov_b32_e32 v5, v4
	v_mov_b32_e32 v6, v4
	v_mov_b32_e32 v7, v4
	v_mov_b32_e32 v16, v4
	v_mov_b32_e32 v17, v4
	v_mov_b32_e32 v18, v4
	v_mov_b32_e32 v19, v4
	v_mov_b32_e32 v40, v4
	v_mov_b32_e32 v41, v4
	v_mov_b32_e32 v42, v4
	v_mov_b32_e32 v43, v4
	v_mov_b32_e32 v48, v4
	v_mov_b32_e32 v49, v4
	v_mov_b32_e32 v50, v4
	v_mov_b32_e32 v51, v4
	v_mov_b32_e32 v52, v4
	v_mov_b32_e32 v53, v4
	v_mov_b32_e32 v54, v4
	v_mov_b32_e32 v55, v4
	v_mov_b32_e32 v32, v4
	v_mov_b32_e32 v33, v4
	v_mov_b32_e32 v34, v4
	v_mov_b32_e32 v35, v4
	v_mov_b32_e32 v20, v4
	v_mov_b32_e32 v21, v4
	v_mov_b32_e32 v22, v4
	v_mov_b32_e32 v23, v4
	v_mov_b32_e32 v8, v4
	v_mov_b32_e32 v9, v4
	v_mov_b32_e32 v10, v4
	v_mov_b32_e32 v11, v4
	v_mov_b32_e32 v24, v4
	v_mov_b32_e32 v25, v4
	v_mov_b32_e32 v26, v4
	v_mov_b32_e32 v27, v4
	v_mov_b32_e32 v12, v4
	v_mov_b32_e32 v13, v4
	v_mov_b32_e32 v14, v4
	v_mov_b32_e32 v15, v4
	v_mov_b32_e32 v28, v4
	v_mov_b32_e32 v29, v4
	v_mov_b32_e32 v30, v4
	v_mov_b32_e32 v31, v4
	v_mov_b32_e32 v36, v4
	v_mov_b32_e32 v37, v4
	v_mov_b32_e32 v38, v4
	v_mov_b32_e32 v39, v4
	v_mov_b32_e32 v44, v4
	v_mov_b32_e32 v45, v4
	v_mov_b32_e32 v46, v4
	v_mov_b32_e32 v47, v4
	v_mov_b32_e32 v56, v4
	v_mov_b32_e32 v57, v4
	v_mov_b32_e32 v58, v4
	v_mov_b32_e32 v59, v4
	v_mov_b32_e32 v60, v4
	v_mov_b32_e32 v61, v4
	v_mov_b32_e32 v62, v4
	v_mov_b32_e32 v63, v4
	v_mov_b32_e32 v64, v4
	v_mov_b32_e32 v65, v4
	v_mov_b32_e32 v66, v4
	v_mov_b32_e32 v67, v4
	s_waitcnt vmcnt(0)
	s_barrier
	v_readfirstlane_b32 s100, v177
	s_add_i32 m0, s100, 0xc000
	v_lshl_add_u64 v[226:227], v[140:141], 0, s[34:35]
	global_load_lds_dwordx4 v[226:227], off
	s_add_i32 m0, s100, 0xd000
	v_lshl_add_u64 v[226:227], v[142:143], 0, s[34:35]
	global_load_lds_dwordx4 v[226:227], off
	s_add_i32 m0, s100, 0xe000
	v_lshl_add_u64 v[226:227], v[144:145], 0, s[34:35]
	global_load_lds_dwordx4 v[226:227], off
	s_add_i32 m0, s100, 0xf000
	v_lshl_add_u64 v[226:227], v[146:147], 0, s[34:35]
	global_load_lds_dwordx4 v[226:227], off
	s_add_i32 m0, s100, 0x8000
	v_lshl_add_u64 v[226:227], v[148:149], 0, s[34:35]
	global_load_lds_dwordx4 v[226:227], off
	s_add_i32 m0, s100, 0x9000
	v_lshl_add_u64 v[226:227], v[150:151], 0, s[34:35]
	global_load_lds_dwordx4 v[226:227], off
	s_add_i32 m0, s100, 0xa000
	v_lshl_add_u64 v[226:227], v[152:153], 0, s[34:35]
	global_load_lds_dwordx4 v[226:227], off
	s_add_i32 m0, s100, 0xb000
	v_lshl_add_u64 v[226:227], v[154:155], 0, s[34:35]
	global_load_lds_dwordx4 v[226:227], off
	v_add_u32_e32 v218, v175, v182
	v_add_u32_e32 v220, v175, v181
	ds_read_b128 v[104:107], v218
	ds_read_b128 v[100:103], v218 offset:2048
	ds_read_b128 v[96:99], v218 offset:4096
	ds_read_b128 v[84:87], v218 offset:6144
	ds_read_b128 v[184:187], v220 offset:16384
	ds_read_b128 v[188:191], v220 offset:18432
	ds_read_b128 v[192:195], v220 offset:20480
	ds_read_b128 v[196:199], v220 offset:22528
; template <int EPI>
; __device__ __forceinline__ void gemm_tile(const bf16_t* __restrict__ A, const int lda, const bf16_t* __restrict__ Bt, const int ldb,
;                                           const int K, const int m0, const int n0, void* Cout, const int ldc, char* lds, const int tid) {
;     ...
;   for (int kt = 0; kt < nt; ++kt) {
;     asm volatile("s_waitcnt vmcnt(0)" ::: "memory");
;     __syncthreads();
;     if (kt + 1 < nt) stageB(kt + 1, (kt + 1) & 1);
;     const char* sa = lds + (kt & 1) * 32768;
;     const char* sb = sa + 16384;
;     bf16x8 af[2][4], bfr[2][4];
; #pragma unroll
;     for (int ks = 0; ks < 2; ++ks) {
; #pragma unroll
;       for (int m = 0; m < 4; ++m) af[ks][m] = *(const bf16x8*)(sa + (wr * 64 + m * 16 + fr) * 128 + (ks ? xk1 : xk0));
; #pragma unroll
;       for (int n = 0; n < 4; ++n) bfr[ks][n] = *(const bf16x8*)(sb + (wc * 64 + n * 16 + fr) * 128 + (ks ? xk1 : xk0));
;     }
;     if (kt + 1 < nt) stageA(kt + 1, (kt + 1) & 1);
; #pragma unroll
;     for (int ks = 0; ks < 2; ++ks)
; #pragma unroll
;       for (int m = 0; m < 4; ++m)
; #pragma unroll
;         for (int n = 0; n < 4; ++n) acc[m][n] = __builtin_amdgcn_mfma_f32_16x16x32_bf16(bfr[ks][n], af[ks][m], acc[m][n], 0, 0, 0);
;   }
.LBB0_649:
	s_add_i32 s24, s25, 0x8000
	s_and_b32 s26, s24, 0x8000
	s_and_b32 s25, s25, 0x8000
	s_waitcnt lgkmcnt(0)
	v_mfma_f32_16x16x32_bf16 v[64:67], v[184:187], v[104:107], v[64:67]
	v_or_b32_e32 v216, s25, v176
	v_add_u32_e32 v222, v216, v182
	v_mfma_f32_16x16x32_bf16 v[60:63], v[188:191], v[104:107], v[60:63]
	v_add_u32_e32 v224, v216, v181
	ds_read_b128 v[200:203], v222
	v_mfma_f32_16x16x32_bf16 v[56:59], v[192:195], v[104:107], v[56:59]
	ds_read_b128 v[204:207], v222 offset:2048
	ds_read_b128 v[92:95], v222 offset:4096
	v_mfma_f32_16x16x32_bf16 v[44:47], v[196:199], v[104:107], v[44:47]
	ds_read_b128 v[68:71], v222 offset:6144
	ds_read_b128 v[88:91], v224 offset:16384
	v_mfma_f32_16x16x32_bf16 v[36:39], v[184:187], v[100:103], v[36:39]
	ds_read_b128 v[80:83], v224 offset:18432
	ds_read_b128 v[72:75], v224 offset:20480
	v_mfma_f32_16x16x32_bf16 v[28:31], v[188:191], v[100:103], v[28:31]
	ds_read_b128 v[76:79], v224 offset:22528
	v_or_b32_e32 v214, s26, v175
	v_mfma_f32_16x16x32_bf16 v[12:15], v[192:195], v[100:103], v[12:15]
	v_add_u32_e32 v218, v214, v182
	v_add_u32_e32 v220, v214, v181
	v_mfma_f32_16x16x32_bf16 v[24:27], v[196:199], v[100:103], v[24:27]
	v_readfirstlane_b32 s100, v177
	s_add_i32 s100, s100, s25
	v_mfma_f32_16x16x32_bf16 v[8:11], v[184:187], v[96:99], v[8:11]
	s_add_u32 s62, s34, 0x80
	s_addc_u32 s63, s35, 0
	v_mfma_f32_16x16x32_bf16 v[20:23], v[188:191], v[96:99], v[20:23]
	v_mfma_f32_16x16x32_bf16 v[32:35], v[192:195], v[96:99], v[32:35]
	v_mfma_f32_16x16x32_bf16 v[52:55], v[196:199], v[96:99], v[52:55]
	v_mfma_f32_16x16x32_bf16 v[48:51], v[184:187], v[84:87], v[48:51]
	v_mfma_f32_16x16x32_bf16 v[40:43], v[188:191], v[84:87], v[40:43]
	v_mfma_f32_16x16x32_bf16 v[16:19], v[192:195], v[84:87], v[16:19]
	v_mfma_f32_16x16x32_bf16 v[4:7], v[196:199], v[84:87], v[4:7]
	s_waitcnt vmcnt(0) lgkmcnt(0)
	s_barrier
	s_cmpk_eq_i32 s34, 0x700
	s_cbranch_scc1 .Lr_last_649
	v_mfma_f32_16x16x32_bf16 v[64:67], v[88:91], v[200:203], v[64:67]
	s_add_i32 m0, s100, 0x4000
	v_lshl_add_u64 v[226:227], v[140:141], 0, s[62:63]
	global_load_lds_dwordx4 v[226:227], off
	v_mfma_f32_16x16x32_bf16 v[60:63], v[80:83], v[200:203], v[60:63]
	s_add_i32 m0, s100, 0x5000
	v_lshl_add_u64 v[226:227], v[142:143], 0, s[62:63]
	global_load_lds_dwordx4 v[226:227], off
	v_mfma_f32_16x16x32_bf16 v[56:59], v[72:75], v[200:203], v[56:59]
	s_add_i32 m0, s100, 0x6000
	v_lshl_add_u64 v[226:227], v[144:145], 0, s[62:63]
	global_load_lds_dwordx4 v[226:227], off
	v_mfma_f32_16x16x32_bf16 v[44:47], v[76:79], v[200:203], v[44:47]
	s_add_i32 m0, s100, 0x7000
	v_lshl_add_u64 v[226:227], v[146:147], 0, s[62:63]
	global_load_lds_dwordx4 v[226:227], off
	v_mfma_f32_16x16x32_bf16 v[36:39], v[88:91], v[204:207], v[36:39]
	s_mov_b32 m0, s100
	v_lshl_add_u64 v[226:227], v[148:149], 0, s[62:63]
	global_load_lds_dwordx4 v[226:227], off
	v_mfma_f32_16x16x32_bf16 v[28:31], v[80:83], v[204:207], v[28:31]
	s_add_i32 m0, s100, 0x1000
	v_lshl_add_u64 v[226:227], v[150:151], 0, s[62:63]
	global_load_lds_dwordx4 v[226:227], off
	v_mfma_f32_16x16x32_bf16 v[12:15], v[72:75], v[204:207], v[12:15]
	s_add_i32 m0, s100, 0x2000
	v_lshl_add_u64 v[226:227], v[152:153], 0, s[62:63]
	global_load_lds_dwordx4 v[226:227], off
	v_mfma_f32_16x16x32_bf16 v[24:27], v[76:79], v[204:207], v[24:27]
	s_add_i32 m0, s100, 0x3000
	v_lshl_add_u64 v[226:227], v[154:155], 0, s[62:63]
	global_load_lds_dwordx4 v[226:227], off
	v_mfma_f32_16x16x32_bf16 v[8:11], v[88:91], v[92:95], v[8:11]
	ds_read_b128 v[104:107], v218
	v_mfma_f32_16x16x32_bf16 v[20:23], v[80:83], v[92:95], v[20:23]
	ds_read_b128 v[100:103], v218 offset:2048
	v_mfma_f32_16x16x32_bf16 v[32:35], v[72:75], v[92:95], v[32:35]
	ds_read_b128 v[96:99], v218 offset:4096
	v_mfma_f32_16x16x32_bf16 v[52:55], v[76:79], v[92:95], v[52:55]
	ds_read_b128 v[84:87], v218 offset:6144
	v_mfma_f32_16x16x32_bf16 v[48:51], v[88:91], v[68:71], v[48:51]
	ds_read_b128 v[184:187], v220 offset:16384
	v_mfma_f32_16x16x32_bf16 v[40:43], v[80:83], v[68:71], v[40:43]
	ds_read_b128 v[188:191], v220 offset:18432
	v_mfma_f32_16x16x32_bf16 v[16:19], v[72:75], v[68:71], v[16:19]
	ds_read_b128 v[192:195], v220 offset:20480
	v_mfma_f32_16x16x32_bf16 v[4:7], v[76:79], v[68:71], v[4:7]
	ds_read_b128 v[196:199], v220 offset:22528
	s_add_u32 s34, s34, 0x80
	s_addc_u32 s35, s35, 0
	s_mov_b32 s25, s24
	s_branch .LBB0_649
.Lr_last_649:
	v_mfma_f32_16x16x32_bf16 v[64:67], v[88:91], v[200:203], v[64:67]
	v_mfma_f32_16x16x32_bf16 v[60:63], v[80:83], v[200:203], v[60:63]
	v_mfma_f32_16x16x32_bf16 v[56:59], v[72:75], v[200:203], v[56:59]
	v_mfma_f32_16x16x32_bf16 v[44:47], v[76:79], v[200:203], v[44:47]
	v_mfma_f32_16x16x32_bf16 v[36:39], v[88:91], v[204:207], v[36:39]
	v_mfma_f32_16x16x32_bf16 v[28:31], v[80:83], v[204:207], v[28:31]
	v_mfma_f32_16x16x32_bf16 v[12:15], v[72:75], v[204:207], v[12:15]
	v_mfma_f32_16x16x32_bf16 v[24:27], v[76:79], v[204:207], v[24:27]
	v_mfma_f32_16x16x32_bf16 v[8:11], v[88:91], v[92:95], v[8:11]
	v_mfma_f32_16x16x32_bf16 v[20:23], v[80:83], v[92:95], v[20:23]
	v_mfma_f32_16x16x32_bf16 v[32:35], v[72:75], v[92:95], v[32:35]
	v_mfma_f32_16x16x32_bf16 v[52:55], v[76:79], v[92:95], v[52:55]
	v_mfma_f32_16x16x32_bf16 v[48:51], v[88:91], v[68:71], v[48:51]
	v_mfma_f32_16x16x32_bf16 v[40:43], v[80:83], v[68:71], v[40:43]
	v_mfma_f32_16x16x32_bf16 v[16:19], v[72:75], v[68:71], v[16:19]
	v_mfma_f32_16x16x32_bf16 v[4:7], v[76:79], v[68:71], v[4:7]
	s_add_u32 s34, s34, 0x80
	s_addc_u32 s35, s35, 0
	s_mov_b32 s25, s24
	v_add_u32_e32 v2, v175, v181
	s_waitcnt vmcnt(0)
	s_waitcnt vmcnt(0) lgkmcnt(0)
	s_barrier
	ds_read_b128 v[68:71], v2 offset:49152
	v_add_u32_e32 v92, v175, v182
	ds_read_b128 v[72:75], v2 offset:51200
	ds_read_b128 v[76:79], v92 offset:32768
	ds_read_b128 v[80:83], v92 offset:34816
	ds_read_b128 v[84:87], v2 offset:53248
	ds_read_b128 v[88:91], v2 offset:55296
	s_waitcnt lgkmcnt(3)
	v_mfma_f32_16x16x32_bf16 v[64:67], v[68:71], v[76:79], v[64:67]
	v_add_u32_e32 v2, v176, v182
	v_add_u32_e32 v104, v176, v181
	s_add_i32 s23, s23, s0
	s_cmpk_lg_i32 s0, 0x200
	s_cbranch_scc1 .Ltail_skip_3
	s_cmpk_lt_i32 s23, 0x1000
	s_cbranch_scc1 .Ltail_skip_3
	s_cmpk_ge_i32 s23, 0x1200
	s_cbranch_scc1 .Ltail_skip_3
	v_readlane_b32 s23, v254, 61
	s_nop 3
	s_addk_i32 s23, 0x1000

; __global__ void __launch_bounds__(256, 2) hymba_fwd(Params p_, int ph_lo, int ph_hi) {
;   __shared__ __attribute__((aligned(16))) char lds[65536];
	.amdhsa_kernel _Z9hymba_fwd6Paramsii
		.amdhsa_group_segment_fixed_size 65536
		.amdhsa_private_segment_fixed_size 0
		.amdhsa_kernarg_size 512
		.amdhsa_user_sgpr_count 2
		.amdhsa_user_sgpr_dispatch_ptr 0
		.amdhsa_user_sgpr_queue_ptr 0
		.amdhsa_user_sgpr_kernarg_segment_ptr 1
		.amdhsa_user_sgpr_dispatch_id 0
		.amdhsa_user_sgpr_kernarg_preload_length 0
		.amdhsa_user_sgpr_kernarg_preload_offset 0
		.amdhsa_user_sgpr_private_segment_size 0
		.amdhsa_uses_dynamic_stack 0
		.amdhsa_enable_private_segment 0
		.amdhsa_system_sgpr_workgroup_id_x 1
		.amdhsa_system_sgpr_workgroup_id_y 0
		.amdhsa_system_sgpr_workgroup_id_z 0
		.amdhsa_system_sgpr_workgroup_info 0
		.amdhsa_system_vgpr_workitem_id 2
		.amdhsa_next_free_vgpr 256
		.amdhsa_next_free_sgpr 102
		.amdhsa_accum_offset 256
		.amdhsa_reserve_vcc 1
		.amdhsa_float_round_mode_32 0
		.amdhsa_float_round_mode_16_64 0
		.amdhsa_float_denorm_mode_32 3
		.amdhsa_float_denorm_mode_16_64 3
		.amdhsa_dx10_clamp 1
		.amdhsa_ieee_mode 1
		.amdhsa_fp16_overflow 0
		.amdhsa_tg_split 0
		.amdhsa_exception_fp_ieee_invalid_op 0
		.amdhsa_exception_fp_denorm_src 0
		.amdhsa_exception_fp_ieee_div_zero 0
		.amdhsa_exception_fp_ieee_overflow 0
		.amdhsa_exception_fp_ieee_underflow 0
		.amdhsa_exception_fp_ieee_inexact 0
		.amdhsa_exception_int_div_zero 0
	.end_amdhsa_kernel

; __global__ void __launch_bounds__(256, 2) hymba_fwd(Params p_, int ph_lo, int ph_hi) {
;   __shared__ __attribute__((aligned(16))) char lds[65536];
amdhsa.kernels:
  - .agpr_count:     0
    .args:
      - .offset:         0
        .size:           248
        .value_kind:     by_value
      - .offset:         248
        .size:           4
        .value_kind:     by_value
      - .offset:         252
        .size:           4
        .value_kind:     by_value
      - .offset:         256
        .size:           4
        .value_kind:     hidden_block_count_x
      - .offset:         260
        .size:           4
        .value_kind:     hidden_block_count_y
      - .offset:         264
        .size:           4
        .value_kind:     hidden_block_count_z
      - .offset:         268
        .size:           2
        .value_kind:     hidden_group_size_x
      - .offset:         270
        .size:           2
        .value_kind:     hidden_group_size_y
      - .offset:         272
        .size:           2
        .value_kind:     hidden_group_size_z
      - .offset:         274
        .size:           2
        .value_kind:     hidden_remainder_x
      - .offset:         276
        .size:           2
        .value_kind:     hidden_remainder_y
      - .offset:         278
        .size:           2
        .value_kind:     hidden_remainder_z
      - .offset:         296
        .size:           8
        .value_kind:     hidden_global_offset_x
      - .offset:         304
        .size:           8
        .value_kind:     hidden_global_offset_y
      - .offset:         312
        .size:           8
        .value_kind:     hidden_global_offset_z
      - .offset:         320
        .size:           2
        .value_kind:     hidden_grid_dims
      - .offset:         344
        .size:           8
        .value_kind:     hidden_multigrid_sync_arg
    .group_segment_fixed_size: 65536
    .kernarg_segment_align: 8
    .kernarg_segment_size: 512
    .language:       OpenCL C
    .language_version:
      - 2
      - 0
    .max_flat_workgroup_size: 256
    .name:           _Z9hymba_fwd6Paramsii
    .private_segment_fixed_size: 0
    .sgpr_count:     108
    .sgpr_spill_count: 298
    .symbol:         _Z9hymba_fwd6Paramsii.kd
    .uniform_work_group_size: 1
    .uses_dynamic_stack: false
    .vgpr_count:     256
    .vgpr_spill_count: 0
    .wavefront_size: 64
